# attention step: per-step row-max chain removed from the main line; one test on the row sum (S <= 256 implies no rescale by the source's rule), otherwise the step is redone by a copy of the original co
# speedup vs baseline: 1.0154x; 1.0102x over previous
; DI float bflo(unsigned u) { return __uint_as_float(u << 16); }
; DI float bfhi(unsigned u) { return __uint_as_float(u & 0xffff0000u); }
; DI void phase_attn(const Params& p, int hf, bool skipctx, char* smem, int& rot) {
;     ...
;     {
;       const float* axc = (const float*)(p.ws + OFF_AXC); const float* axs = (const float*)(p.ws + OFF_AXS);
;       uint4 qu[6];
; #pragma unroll
;       for (int ks = 0; ks < 6; ++ks) qu[ks] = *(const uint4*)(Qb + tq * 768 + head * 96 + ks * 16 + h * 8);
; #pragma unroll
;       for (int ks = 0; ks < 4; ++ks) {
;         const uint4 u = qu[ks];
;         qf[ks] = pack8(bflo(u.x) * QSCALE, bfhi(u.x) * QSCALE, bflo(u.y) * QSCALE, bfhi(u.y) * QSCALE, bflo(u.z) * QSCALE, bfhi(u.z) * QSCALE, bflo(u.w) * QSCALE, bfhi(u.w) * QSCALE);
;       }
;       const unsigned a1[4] = {qu[4].x, qu[4].y, qu[4].z, qu[4].w}, a2[4] = {qu[5].x, qu[5].y, qu[5].z, qu[5].w};
;       float o1[8], o2[8];
;       const int sq_ = s0 + w * 32 + r;
; #pragma unroll
;       for (int e = 0; e < 8; ++e) {
;         const float x1 = ((e & 1) ? bfhi(a1[e >> 1]) : bflo(a1[e >> 1])) * QSCALE;
;         const float x2 = ((e & 1) ? bfhi(a2[e >> 1]) : bflo(a2[e >> 1])) * QSCALE;
;         float cs = 1.f, sn = 0.f;
;         if (sq_ >= LC) { cs = axc[(sq_ - LC) * 16 + 8 * h + e]; sn = axs[(sq_ - LC) * 16 + 8 * h + e]; }
;         o1[e] = x1 * cs - x2 * sn; o2[e] = x1 * sn + x2 * cs;
;       }
;       qf[4] = pack8(o1[0], o1[1], o1[2], o1[3], o1[4], o1[5], o1[6], o1[7]);
;       qf[5] = pack8(o2[0], o2[1], o2[2], o2[3], o2[4], o2[5], o2[6], o2[7]);
;     }
;     ...
;     const int kr0 = tid / 12, kc0 = tid - kr0 * 12, kr1 = (tid + 512) / 12, kc1 = (tid + 512) - kr1 * 12, kr2 = (tid + 1024) / 12, kc2 = (tid + 1024) - kr2 * 12;
;     const int vr0 = tid >> 4, vr1 = (tid + 512) >> 4, vc = tid & 15;
.LBB0_794:
	s_or_b64 exec, exec, s[26:27]
	s_waitcnt vmcnt(0)
	v_lshlrev_b32_e32 v27, 16, v23
	v_lshlrev_b32_e32 v26, 16, v19
	v_pk_mul_f32 v[26:27], v[26:27], s[48:49] op_sel_hi:[1,0]
	v_lshlrev_b32_e32 v47, 16, v22
	v_pk_mul_f32 v[28:29], v[26:27], v[30:31] op_sel:[0,1] op_sel_hi:[1,0]
	v_pk_mul_f32 v[26:27], v[26:27], v[30:31]
	v_and_b32_e32 v30, 0xffff0000, v19
	v_lshlrev_b32_e32 v46, 16, v18
	v_and_b32_e32 v19, 0xffff0000, v22
	v_and_b32_e32 v18, 0xffff0000, v18
	v_and_b32_e32 v31, 0xffff0000, v23
	v_pk_mul_f32 v[46:47], v[46:47], s[48:49] op_sel_hi:[1,0]
	v_pk_mul_f32 v[22:23], v[18:19], s[48:49] op_sel_hi:[1,0]
	v_pk_mul_f32 v[48:49], v[46:47], v[42:43] op_sel:[0,1] op_sel_hi:[1,0]
	v_pk_mul_f32 v[42:43], v[46:47], v[42:43]
	v_pk_mul_f32 v[18:19], v[22:23], v[40:41] op_sel:[0,1] op_sel_hi:[1,0]
	v_pk_mul_f32 v[22:23], v[22:23], v[40:41]
	v_mov_b32_e32 v40, v42
	v_mov_b32_e32 v41, v22
	v_mov_b32_e32 v22, v43
	v_pk_add_f32 v[22:23], v[40:41], v[22:23]
	v_lshlrev_b32_e32 v41, 16, v21
	v_lshlrev_b32_e32 v40, 16, v17
	v_pk_mul_f32 v[40:41], v[40:41], s[48:49] op_sel_hi:[1,0]
	v_mov_b32_e32 v46, v48
	v_mov_b32_e32 v47, v18
	v_mov_b32_e32 v18, v49
	v_pk_mul_f32 v[42:43], v[40:41], v[32:33] op_sel:[0,1] op_sel_hi:[1,0]
	v_pk_mul_f32 v[40:41], v[40:41], v[32:33]
	v_and_b32_e32 v33, 0xffff0000, v21
	v_and_b32_e32 v32, 0xffff0000, v17
	v_pk_add_f32 v[18:19], v[46:47], v[18:19] neg_lo:[0,1] neg_hi:[0,1]
	v_pk_mul_f32 v[46:47], v[32:33], s[48:49] op_sel_hi:[1,0]
	v_mov_b32_e32 v48, v42
	v_pk_mul_f32 v[32:33], v[46:47], v[34:35] op_sel:[0,1] op_sel_hi:[1,0]
	v_pk_mul_f32 v[34:35], v[46:47], v[34:35]
	v_mov_b32_e32 v49, v32
	v_mov_b32_e32 v32, v43
	v_mov_b32_e32 v42, v40
	v_mov_b32_e32 v43, v34
	v_mov_b32_e32 v34, v41
	v_lshlrev_b32_e32 v41, 16, v20
	v_lshlrev_b32_e32 v40, 16, v16
	v_and_b32_e32 v17, 0xffff0000, v20
	v_and_b32_e32 v16, 0xffff0000, v16
	v_pk_mul_f32 v[40:41], v[40:41], s[48:49] op_sel_hi:[1,0]
	v_pk_mul_f32 v[20:21], v[16:17], s[48:49] op_sel_hi:[1,0]
	v_pk_add_f32 v[34:35], v[42:43], v[34:35]
	v_pk_mul_f32 v[42:43], v[40:41], v[38:39] op_sel:[0,1] op_sel_hi:[1,0]
	v_pk_mul_f32 v[38:39], v[40:41], v[38:39]
	v_pk_mul_f32 v[16:17], v[20:21], v[36:37] op_sel:[0,1] op_sel_hi:[1,0]
	v_pk_mul_f32 v[20:21], v[20:21], v[36:37]
	v_mov_b32_e32 v36, v38
	v_mov_b32_e32 v37, v20
	v_mov_b32_e32 v20, v39
	v_pk_add_f32 v[20:21], v[36:37], v[20:21]
	v_lshlrev_b32_e32 v36, 16, v12
	v_and_b32_e32 v37, 0xffff0000, v12
	v_lshlrev_b32_e32 v12, 16, v13
	v_and_b32_e32 v13, 0xffff0000, v13
	v_pk_mul_f32 v[12:13], v[12:13], s[48:49] op_sel_hi:[1,0]
	v_lshlrev_b32_e32 v38, 16, v14
	v_cvt_pk_bf16_f32 v65, v12, v13
	v_lshlrev_b32_e32 v12, 16, v8
	v_and_b32_e32 v13, 0xffff0000, v8
	v_lshlrev_b32_e32 v8, 16, v9
	v_and_b32_e32 v9, 0xffff0000, v9
	v_pk_mul_f32 v[8:9], v[8:9], s[48:49] op_sel_hi:[1,0]
	v_and_b32_e32 v39, 0xffff0000, v14
	v_cvt_pk_bf16_f32 v69, v8, v9
	v_lshlrev_b32_e32 v8, 16, v4
	v_and_b32_e32 v9, 0xffff0000, v4
	v_lshlrev_b32_e32 v4, 16, v5
	v_and_b32_e32 v5, 0xffff0000, v5
	v_lshlrev_b32_e32 v14, 16, v15
	v_and_b32_e32 v15, 0xffff0000, v15
	v_pk_mul_f32 v[4:5], v[4:5], s[48:49] op_sel_hi:[1,0]
	s_mov_b32 s16, 0x2aaaaaab
	v_pk_mul_f32 v[14:15], v[14:15], s[48:49] op_sel_hi:[1,0]
	v_cvt_pk_bf16_f32 v73, v4, v5
	v_mul_hi_i32 v4, v160, s16
	v_cvt_pk_bf16_f32 v67, v14, v15
	v_lshlrev_b32_e32 v14, 16, v10
	v_and_b32_e32 v15, 0xffff0000, v10
	v_lshlrev_b32_e32 v10, 16, v11
	v_and_b32_e32 v11, 0xffff0000, v11
	v_lshrrev_b32_e32 v5, 31, v4
	v_ashrrev_i32_e32 v4, 1, v4
	v_pk_mul_f32 v[10:11], v[10:11], s[48:49] op_sel_hi:[1,0]
	v_add_u32_e32 v45, v4, v5
	v_cvt_pk_bf16_f32 v71, v10, v11
	v_lshlrev_b32_e32 v10, 16, v6
	v_and_b32_e32 v11, 0xffff0000, v6
	v_lshlrev_b32_e32 v6, 16, v7
	v_and_b32_e32 v7, 0xffff0000, v7
	v_mad_u64_u32 v[4:5], s[38:39], v45, -12, v[160:161]
	v_add_u32_e32 v164, 0x200, v160
	v_pk_mul_f32 v[6:7], v[6:7], s[48:49] op_sel_hi:[1,0]
	v_mul_hi_i32 v5, v164, s16
	v_cvt_pk_bf16_f32 v75, v6, v7
	v_lshrrev_b32_e32 v6, 31, v5
	v_ashrrev_i32_e32 v5, 1, v5
	s_mul_i32 s15, s4, 0xcc000
	v_add_u32_e32 v5, v5, v6
	v_pk_mul_f32 v[38:39], v[38:39], s[48:49] op_sel_hi:[1,0]
	v_pk_mul_f32 v[14:15], v[14:15], s[48:49] op_sel_hi:[1,0]
	s_mul_hi_i32 s5, s4, 0xcc000
	s_add_u32 s26, s90, s15
	v_mad_u64_u32 v[6:7], s[38:39], v5, -12, v[164:165]
	v_add_u32_e32 v162, 0x400, v160
	v_cvt_pk_bf16_f32 v66, v38, v39
	v_cvt_pk_bf16_f32 v70, v14, v15
	v_pk_mul_f32 v[8:9], v[8:9], s[48:49] op_sel_hi:[1,0]
	v_pk_mul_f32 v[10:11], v[10:11], s[48:49] op_sel_hi:[1,0]
	s_addc_u32 s27, s91, s5
	v_mul_hi_i32 v7, v162, s16
	v_lshlrev_b32_e32 v14, 3, v4
	v_lshlrev_b32_e32 v38, 3, v6
	v_pk_mul_f32 v[36:37], v[36:37], s[48:49] op_sel_hi:[1,0]
	v_pk_mul_f32 v[12:13], v[12:13], s[48:49] op_sel_hi:[1,0]
	v_cvt_pk_bf16_f32 v72, v8, v9
	v_cvt_pk_bf16_f32 v74, v10, v11
	v_lshrrev_b32_e32 v8, 31, v7
	v_ashrrev_i32_e32 v7, 1, v7
	v_mov_b64_e32 v[10:11], s[26:27]
	v_ashrrev_i32_e32 v15, 31, v14
	v_ashrrev_i32_e32 v39, 31, v38
	v_cvt_pk_bf16_f32 v64, v36, v37
	v_cvt_pk_bf16_f32 v68, v12, v13
	v_add_u32_e32 v7, v7, v8
	v_mad_i64_i32 v[12:13], s[26:27], v45, s17, v[10:11]
	v_lshlrev_b64 v[14:15], 1, v[14:15]
	v_mad_i64_i32 v[36:37], s[26:27], v5, s17, v[10:11]
	v_lshlrev_b64 v[38:39], 1, v[38:39]
	v_mad_u64_u32 v[8:9], s[38:39], v7, -12, v[162:163]
	v_lshl_add_u64 v[12:13], v[12:13], 0, v[14:15]
	v_lshl_add_u64 v[36:37], v[36:37], 0, v[38:39]
	s_barrier
; DI void phase_attn(const Params& p, int hf, bool skipctx, char* smem, int& rot) {
;     ...
;     const int kr0 = tid / 12, kc0 = tid - kr0 * 12, kr1 = (tid + 512) / 12, kc1 = (tid + 512) - kr1 * 12, kr2 = (tid + 1024) / 12, kc2 = (tid + 1024) - kr2 * 12;
;     const int vr0 = tid >> 4, vr1 = (tid + 512) >> 4, vc = tid & 15;
;     ...
;     ATT_LOAD(ak0, ak1, ak2, av0, av1, 0);
;     ATT_LOAD(bk0, bk1, bk2, bv0, bv1, 1);
	global_load_dwordx4 v[76:79], v[12:13], off
	global_load_dwordx4 v[80:83], v[36:37], off
	v_lshlrev_b32_e32 v36, 3, v8
	s_mul_i32 s15, s4, 0x88000
	v_readlane_b32 s36, v252, 5
	v_ashrrev_i32_e32 v37, 31, v36
	s_mul_hi_i32 s5, s4, 0x88000
	v_readlane_b32 s37, v252, 6
	s_add_u32 s36, s36, s15
	v_mad_i64_i32 v[12:13], s[26:27], v7, s17, v[10:11]
	v_lshlrev_b64 v[36:37], 1, v[36:37]
	s_addc_u32 s37, s37, s5
	v_lshl_add_u64 v[12:13], v[12:13], 0, v[36:37]
	v_mov_b32_e32 v40, v42
	v_mov_b32_e32 v41, v16
	v_mov_b32_e32 v16, v43
	v_ashrrev_i32_e32 v9, 4, v160
	v_ashrrev_i32_e32 v50, 4, v164
	global_load_dwordx4 v[84:87], v[12:13], off
	v_mov_b64_e32 v[12:13], s[36:37]
	s_movk_i32 s16, 0x2200
	v_lshlrev_b32_e32 v165, 4, v160
	v_cvt_pk_bf16_f32 v100, v20, v21
	v_add_u32_e32 v20, 0x80, v5
	v_pk_add_f32 v[16:17], v[40:41], v[16:17] neg_lo:[0,1] neg_hi:[0,1]
	v_mad_i64_i32 v[40:41], s[26:27], v9, s16, v[12:13]
	v_and_b32_e32 v42, 0xf0, v165
	v_mov_b32_e32 v43, v221
	v_mad_i64_i32 v[12:13], s[26:27], v50, s16, v[12:13]
	v_cvt_pk_bf16_f32 v98, v18, v19
	v_cvt_pk_bf16_f32 v102, v22, v23
	v_add_u32_e32 v18, 0x80, v45
	v_mad_i64_i32 v[20:21], s[26:27], v20, s17, v[10:11]
	v_add_u32_e32 v22, 0x80, v7
	v_lshl_add_u64 v[40:41], v[40:41], 0, v[42:43]
	v_lshl_add_u64 v[12:13], v[12:13], 0, v[42:43]
	v_mad_i64_i32 v[18:19], s[26:27], v18, s17, v[10:11]
	v_lshl_add_u64 v[20:21], v[20:21], 0, v[38:39]
	v_mad_i64_i32 v[10:11], s[26:27], v22, s17, v[10:11]
	global_load_dwordx4 v[92:95], v[40:41], off
	global_load_dwordx4 v[104:107], v[12:13], off
	v_lshl_add_u64 v[18:19], v[18:19], 0, v[14:15]
	v_lshl_add_u64 v[10:11], v[10:11], 0, v[36:37]
	global_load_dwordx4 v[108:111], v[20:21], off
	global_load_dwordx4 v[116:119], v[10:11], off
	global_load_dwordx4 v[120:123], v[40:41], off offset:256
	global_load_dwordx4 v[112:115], v[18:19], off
	global_load_dwordx4 v[124:127], v[12:13], off offset:256
	v_lshlrev_b32_e32 v46, 16, v0
	v_and_b32_e32 v47, 0xffff0000, v0
	v_lshlrev_b32_e32 v0, 16, v1
	v_and_b32_e32 v1, 0xffff0000, v1
	v_pk_mul_f32 v[30:31], v[30:31], s[48:49] op_sel_hi:[1,0]
	v_pk_add_f32 v[32:33], v[48:49], v[32:33] neg_lo:[0,1] neg_hi:[0,1]
	v_pk_mul_f32 v[0:1], v[0:1], s[48:49] op_sel_hi:[1,0]
	v_lshlrev_b32_e32 v48, 16, v2
	v_and_b32_e32 v49, 0xffff0000, v2
	v_lshlrev_b32_e32 v2, 16, v3
	v_and_b32_e32 v3, 0xffff0000, v3
	v_pk_mul_f32 v[2:3], v[2:3], s[48:49] op_sel_hi:[1,0]
	v_cvt_pk_bf16_f32 v89, v0, v1
	v_pk_mul_f32 v[0:1], v[30:31], v[24:25] op_sel:[0,1] op_sel_hi:[1,0]
	v_cvt_pk_bf16_f32 v91, v2, v3
	v_mov_b32_e32 v2, v28
	v_mov_b32_e32 v3, v0
	v_mov_b32_e32 v0, v29
	v_pk_add_f32 v[0:1], v[2:3], v[0:1] neg_lo:[0,1] neg_hi:[0,1]
	v_pk_mul_f32 v[2:3], v[30:31], v[24:25]
	v_mul_lo_u32 v10, v45, s97
	v_mov_b32_e32 v24, v26
	v_mov_b32_e32 v25, v2
	v_mov_b32_e32 v2, v27
	v_add_u32_e32 v10, 0, v10
	v_lshlrev_b32_e32 v4, 4, v4
	v_pk_add_f32 v[2:3], v[24:25], v[2:3]
	v_add_u32_e32 v176, v10, v4
	v_mul_lo_u32 v4, v5, s97
	v_cvt_pk_bf16_f32 v103, v2, v3
	v_mad_i64_i32 v[2:3], s[26:27], v5, s17, 0
	v_add_u32_e32 v4, 0, v4
	v_lshlrev_b32_e32 v5, 4, v6
	v_add_u32_e32 v177, v4, v5
	v_mul_lo_u32 v4, v7, s97
	v_add_u32_e32 v4, 0, v4
	v_lshlrev_b32_e32 v5, 4, v8
	s_movk_i32 s20, 0x108
	v_cvt_pk_bf16_f32 v96, v16, v17
	v_cvt_pk_bf16_f32 v99, v0, v1
	v_mad_i64_i32 v[0:1], s[26:27], v45, s17, 0
	v_mad_i64_i32 v[16:17], s[26:27], v7, s17, 0
	v_add_u32_e32 v178, v4, v5
	v_mul_lo_u32 v4, v9, s20
	v_add_u32_e32 v5, 0, v4
	s_movk_i32 s26, 0x6800
	v_add3_u32 v179, v5, v42, s26
	v_mul_lo_u32 v5, v50, s20
	v_add_u32_e32 v6, 0, v5
	v_add3_u32 v180, v6, v42, s26
	v_or_b32_e32 v181, 32, v161
	v_or_b32_e32 v182, 64, v161
	v_or_b32_e32 v183, 0x60, v161
	v_readlane_b32 s26, v254, 35
	v_mul_u32_u24_e32 v19, 0x108, v44
	v_mad_u32_u24 v18, v44, s97, 0
	v_add_u32_e32 v21, s26, v4
	v_add_u32_e32 v22, s26, v5
	v_add_u32_e32 v23, s26, v161
	v_add_u32_e32 v24, s26, v181
	v_mov_b32_e32 v4, s26
	v_add_u32_e32 v25, s26, v182
	v_add_u32_e32 v26, s26, v183
	v_readlane_b32 s26, v254, 36
	v_mad_u32_u24 v184, v44, s20, v4
	v_add_u32_e32 v20, 0, v161
	v_add_u32_e32 v27, s26, v161
	v_add_u32_e32 v28, s26, v181
	v_mov_b32_e32 v4, s26
	v_add_u32_e32 v29, s26, v182
	v_add_u32_e32 v30, s26, v183
	s_add_u32 s26, s15, 0x1a49c300
	s_addc_u32 s27, s5, 0
	v_mad_u32_u24 v185, v44, s20, v4
	v_mov_b64_e32 v[4:5], s[26:27]
	v_mad_i64_i32 v[166:167], s[26:27], v9, s16, v[4:5]
	v_mad_i64_i32 v[168:169], s[26:27], v50, s16, v[4:5]
	v_mad_i64_i32 v[4:5], s[26:27], s4, v231, v[16:17]
	v_mad_i64_i32 v[2:3], s[26:27], s4, v231, v[2:3]
	v_mad_i64_i32 v[0:1], s[4:5], s4, v231, v[0:1]
	v_lshl_add_u64 v[174:175], v[0:1], 0, v[14:15]
	v_mov_b32_e32 v14, v221
	v_mov_b32_e32 v15, v221
	v_add_u32_e32 v186, v21, v42
	v_add_u32_e32 v187, v22, v42
	v_add_u32_e32 v188, v23, v19
	v_add_u32_e32 v16, v24, v19
	v_add_u32_e32 v17, v25, v19
	v_add_u32_e32 v21, v26, v19
	v_add_u32_e32 v22, v28, v19
	v_add_u32_e32 v23, v29, v19
	v_add_u32_e32 v24, v30, v19
	v_pk_mul_f32 v[46:47], v[46:47], s[48:49] op_sel_hi:[1,0]
	v_pk_mul_f32 v[48:49], v[48:49], s[48:49] op_sel_hi:[1,0]
	v_lshl_add_u64 v[170:171], v[4:5], 0, v[36:37]
	v_lshl_add_u64 v[172:173], v[2:3], 0, v[38:39]
	v_mov_b32_e32 v0, v221
	v_mov_b32_e32 v1, v221
	v_mov_b32_e32 v2, v221
	v_mov_b32_e32 v3, v221
	v_mov_b32_e32 v4, v221
	v_mov_b32_e32 v5, v221
	v_mov_b32_e32 v6, v221
	v_mov_b32_e32 v7, v221
	v_mov_b32_e32 v8, v221
	v_mov_b32_e32 v9, v221
	v_mov_b32_e32 v10, v221
	v_mov_b32_e32 v11, v221
	v_mov_b32_e32 v12, v221
	v_mov_b32_e32 v13, v221
	v_add_u32_e32 v189, v27, v19
	v_add_u32_e32 v190, v18, v220
	v_add_u32_e32 v191, v20, v19
	v_add_u32_e32 v194, 0x2000, v16
	v_add_u32_e32 v204, 0x2000, v17
	v_add_u32_e32 v206, 0x2000, v21
	v_add_u32_e32 v208, 0x2000, v22
	v_add_u32_e32 v210, 0x2000, v23
	v_add_u32_e32 v211, 0x2000, v24
	v_mov_b64_e32 v[30:31], v[14:15]
	v_cvt_pk_bf16_f32 v88, v46, v47
	v_cvt_pk_bf16_f32 v90, v48, v49
	v_cvt_pk_bf16_f32 v97, v32, v33
	v_cvt_pk_bf16_f32 v101, v34, v35
	v_or_b32_e32 v166, v166, v42
	v_or_b32_e32 v168, v168, v42
	s_mov_b32 s4, 0
	v_mov_b32_e32 v212, 0xf149f2ca
	v_mov_b32_e32 v213, 0
	v_mov_b64_e32 v[28:29], v[12:13]
	v_mov_b64_e32 v[26:27], v[10:11]
	v_mov_b64_e32 v[24:25], v[8:9]
	v_mov_b64_e32 v[22:23], v[6:7]
	v_mov_b64_e32 v[20:21], v[4:5]
	v_mov_b64_e32 v[18:19], v[2:3]
	v_mov_b64_e32 v[16:17], v[0:1]
	v_and_b32_e32 v200, 15, v192
	v_lshrrev_b32_e32 v201, 4, v192
	v_mul_u32_u24_e32 v179, 0x110, v201
	v_lshrrev_b32_e32 v202, 1, v200
	v_lshl_add_u32 v179, v202, 5, v179
	v_and_b32_e32 v202, 1, v200
	v_lshl_add_u32 v179, v202, 3, v179
	v_add_u32_e32 v179, 0x6800, v179
	v_add_u32_e32 v180, 0x2200, v179
	v_add_u32_e32 v186, 0xac00, v179
	v_add_u32_e32 v187, 0xac00, v180
	v_and_b32_e32 v200, 31, v192
	v_bfe_u32 v201, v192, 5, 1
	v_mul_u32_u24_e32 v191, 0x110, v200
	v_lshl_add_u32 v191, v201, 4, v191
	v_add_u32_e32 v191, 0x6800, v191
	s_waitcnt vmcnt(9)
; DI f32x16 zero16() { f32x16 z; for (int i = 0; i < 16; ++i) z[i] = 0.f; return z; }
; DI void phase_attn(const Params& p, int hf, bool skipctx, char* smem, int& rot) {
;     ...
;     f32x16 o[2]; o[0] = zero16(); o[1] = zero16();
;     float m_run = -1e30f, l_run = 0.f;
;     ...
;     __syncthreads();
;     ATT_LOAD(ak0, ak1, ak2, av0, av1, 0);
;     ATT_LOAD(bk0, bk1, bk2, bv0, bv1, 1);
;     ATT_WRITE(ak0, ak1, ak2, av0, av1, 0);
;     __syncthreads();
	ds_write_b128 v176, v[76:79]
	s_waitcnt vmcnt(8)
	ds_write_b128 v177, v[80:83]
	s_waitcnt vmcnt(7)
	ds_write_b128 v178, v[84:87]
	s_waitcnt vmcnt(6)
	ds_write_b64 v179, v[92:93] offset:0
	ds_write_b64 v179, v[94:95] offset:16
	s_waitcnt vmcnt(5)
	ds_write_b64 v179, v[104:105] offset:8704
	ds_write_b64 v179, v[106:107] offset:8720
	s_waitcnt lgkmcnt(0)
	s_barrier
	v_mov_b32_e32 v194, v176
	v_mov_b32_e32 v204, v177
	v_mov_b32_e32 v206, v178
	v_mov_b32_e32 v208, v179
	v_mov_b32_e32 v210, v190
	v_mov_b32_e32 v211, v191
	v_mov_b32_e32 v220, 0xf149f2ca
	v_mov_b32_e32 v176, 0
	v_mov_b32_e32 v177, 0
	v_mov_b32_e32 v178, 0
	v_mov_b32_e32 v179, 0
	v_mov_b32_e32 v180, 0
	v_mov_b32_e32 v181, 0
	v_mov_b32_e32 v182, 0
	v_mov_b32_e32 v183, 0
	v_mov_b32_e32 v184, 0
	v_mov_b32_e32 v185, 0
	v_mov_b32_e32 v186, 0
	v_mov_b32_e32 v187, 0
	v_mov_b32_e32 v188, 0
	v_mov_b32_e32 v189, 0
	v_mov_b32_e32 v190, 0
	v_mov_b32_e32 v191, 0
	v_add_u32_e32 v170, 0x18b28000, v170
	v_add_u32_e32 v172, 0x18b28000, v172
	v_add_u32_e32 v174, 0x18b28000, v174
	v_mov_b32_e32 v167, 0xbf800000

; DI float fexp2(float x) { return __builtin_amdgcn_exp2f(x); }
; DI void phase_attn(const Params& p, int hf, bool skipctx, char* smem, int& rot) {
;     ...
;     auto compute = [&](int buf, int half) {
;       const char* sk = smem + buf * STG + half * 64 * KROW; const char* sv = smem + buf * STG + KB_ + half * 128;
;       f32x16 st[2]; st[0] = zero16(); st[1] = zero16();
;       {
;         bf16x8 kf[2][6];
; #pragma unroll
;         for (int kb = 0; kb < 2; ++kb)
; #pragma unroll
;           for (int ks = 0; ks < 6; ++ks) kf[kb][ks] = *(const bf16x8*)(sk + (kb * 32 + r) * KROW + (ks * 16 + h * 8) * 2);
;         __builtin_amdgcn_sched_barrier(0);
; #pragma unroll
;         for (int ks = 0; ks < 6; ++ks)
; #pragma unroll
;           for (int kb = 0; kb < 2; ++kb) st[kb] = MFMA(kf[kb][ks], qf[ks], st[kb]);
;         __builtin_amdgcn_sched_barrier(0);
;       }
;       bf16x8 vf[2][2][2];
; #pragma unroll
;       for (int kb = 0; kb < 2; ++kb)
; #pragma unroll
;         for (int s2 = 0; s2 < 2; ++s2)
; #pragma unroll
;           for (int dvb = 0; dvb < 2; ++dvb) {
;             const char* vp = sv + (dvb * 32 + r) * VROW + (kb * 32 + 16 * s2 + 4 * h) * 2;
;             const s16x4 lo = *(const s16x4*)vp, hi = *(const s16x4*)(vp + 16);
;             vf[kb][s2][dvb] = __builtin_shufflevector(lo, hi, 0, 1, 2, 3, 4, 5, 6, 7);
;           }
;       float mx = st[0][0];
; #pragma unroll
;       for (int i = 0; i < 16; ++i) { mx = fmaxf(mx, st[0][i]); mx = fmaxf(mx, st[1][i]); }
;       if (__any(mx > m_run + 8.f)) {
;         mx = fmaxf(mx, __shfl_xor(mx, 32));
;         const float m_new = fmaxf(m_run, mx);
;         const float alpha = fexp2(m_run - m_new);
;         m_run = m_new;
;         l_run *= alpha;
; #pragma unroll
;         for (int i = 0; i < 16; ++i) { o[0][i] *= alpha; o[1][i] *= alpha; }
;       }
;       float ps = 0.f;
; #pragma unroll
;       for (int kb = 0; kb < 2; ++kb)
; #pragma unroll
;         for (int i = 0; i < 16; ++i) { const float e = fexp2(st[kb][i] - m_run); st[kb][i] = e; ps += e; }
;       l_run += ps;
; #pragma unroll
;       for (int kb = 0; kb < 2; ++kb)
; #pragma unroll
;         for (int s2 = 0; s2 < 2; ++s2) {
;           const bf16x8 pb = pack8(st[kb][8 * s2 + 0], st[kb][8 * s2 + 1], st[kb][8 * s2 + 2], st[kb][8 * s2 + 3], st[kb][8 * s2 + 4], st[kb][8 * s2 + 5], st[kb][8 * s2 + 6], st[kb][8 * s2 + 7]);
; #pragma unroll
.LBB0_797:
	s_waitcnt lgkmcnt(11)
	v_mfma_f32_32x32x16_bf16 v[48:63], v[32:35], v[64:67], v[176:191]
	s_waitcnt lgkmcnt(5)
	v_mfma_f32_32x32x16_bf16 v[32:47], v[36:39], v[64:67], v[176:191]
	v_mfma_f32_32x32x16_bf16 v[48:63], v[128:131], v[68:71], v[48:63]
	s_waitcnt lgkmcnt(4)
	v_mfma_f32_32x32x16_bf16 v[32:47], v[148:151], v[68:71], v[32:47]
	v_mfma_f32_32x32x16_bf16 v[48:63], v[132:135], v[72:75], v[48:63]
	s_waitcnt lgkmcnt(3)
	v_mfma_f32_32x32x16_bf16 v[32:47], v[152:155], v[72:75], v[32:47]
	v_mfma_f32_32x32x16_bf16 v[48:63], v[136:139], v[88:91], v[48:63]
	s_waitcnt lgkmcnt(2)
	v_mfma_f32_32x32x16_bf16 v[32:47], v[156:159], v[88:91], v[32:47]
	v_mfma_f32_32x32x16_bf16 v[48:63], v[140:143], v[96:99], v[48:63]
	s_waitcnt lgkmcnt(1)
	v_mfma_f32_32x32x16_bf16 v[32:47], v[214:217], v[96:99], v[32:47]
	v_mfma_f32_32x32x16_bf16 v[48:63], v[144:147], v[100:103], v[48:63]
	s_waitcnt lgkmcnt(0)
	v_mfma_f32_32x32x16_bf16 v[32:47], v[234:237], v[100:103], v[32:47]
	s_nop 3
	ds_read_b128 v[156:159], v211 offset:0
	ds_read_b128 v[148:151], v211 offset:32
	ds_read_b128 v[152:155], v211 offset:8704
	ds_read_b128 v[144:147], v211 offset:8736
	ds_read_b128 v[140:143], v211 offset:64
	ds_read_b128 v[136:139], v211 offset:8768
	ds_read_b128 v[132:135], v211 offset:96
	ds_read_b128 v[128:131], v211 offset:8800
	v_exp_f32_e32 v48, v48
	v_exp_f32_e32 v49, v49
	v_exp_f32_e32 v50, v50
	v_exp_f32_e32 v51, v51
	v_exp_f32_e32 v52, v52
	v_exp_f32_e32 v53, v53
	v_exp_f32_e32 v54, v54
	v_exp_f32_e32 v55, v55
	v_exp_f32_e32 v56, v56
	v_exp_f32_e32 v57, v57
	v_exp_f32_e32 v58, v58
	v_exp_f32_e32 v59, v59
	v_exp_f32_e32 v60, v60
	v_exp_f32_e32 v61, v61
	v_exp_f32_e32 v62, v62
	v_exp_f32_e32 v63, v63
	v_exp_f32_e32 v32, v32
	v_exp_f32_e32 v33, v33
	v_exp_f32_e32 v34, v34
	v_exp_f32_e32 v35, v35
	v_exp_f32_e32 v36, v36
	v_exp_f32_e32 v37, v37
	v_exp_f32_e32 v38, v38
	v_exp_f32_e32 v39, v39
	v_exp_f32_e32 v40, v40
	v_exp_f32_e32 v41, v41
	v_exp_f32_e32 v42, v42
	v_exp_f32_e32 v43, v43
	v_exp_f32_e32 v44, v44
	v_exp_f32_e32 v45, v45
	v_exp_f32_e32 v46, v46
	v_exp_f32_e32 v47, v47
	v_add_f32_e32 v195, v48, v49
	v_add_f32_e32 v195, v195, v50
	v_add_f32_e32 v195, v195, v51
	v_add_f32_e32 v195, v195, v52
	v_add_f32_e32 v195, v195, v53
	v_add_f32_e32 v195, v195, v54
	v_add_f32_e32 v195, v195, v55
	v_add_f32_e32 v195, v195, v56
	v_add_f32_e32 v195, v195, v57
	v_add_f32_e32 v195, v195, v58
	v_add_f32_e32 v195, v195, v59
	v_add_f32_e32 v195, v195, v60
	v_add_f32_e32 v195, v195, v61
	v_add_f32_e32 v195, v195, v62
	v_add_f32_e32 v195, v195, v63
	v_add_f32_e32 v195, v195, v32
	v_add_f32_e32 v195, v195, v33
	v_add_f32_e32 v195, v195, v34
	v_add_f32_e32 v195, v195, v35
	v_add_f32_e32 v195, v195, v36
	v_add_f32_e32 v195, v195, v37
	v_add_f32_e32 v195, v195, v38
	v_add_f32_e32 v195, v195, v39
	v_add_f32_e32 v195, v195, v40
	v_add_f32_e32 v195, v195, v41
	v_add_f32_e32 v195, v195, v42
	v_add_f32_e32 v195, v195, v43
	v_add_f32_e32 v195, v195, v44
	v_add_f32_e32 v195, v195, v45
	v_add_f32_e32 v195, v195, v46
	v_add_f32_e32 v195, v195, v47
	v_cmp_nle_f32_e32 vcc, v195, v167
	s_cbranch_vccnz .Lsc0_fb0
	v_add_f32_e32 v213, v213, v195
	v_cvt_pk_bf16_f32 v48, v48, v49
	v_cvt_pk_bf16_f32 v49, v50, v51
	v_cvt_pk_bf16_f32 v50, v52, v53
	v_cvt_pk_bf16_f32 v51, v54, v55
	v_cvt_pk_bf16_f32 v52, v56, v57
	v_cvt_pk_bf16_f32 v53, v58, v59
	v_cvt_pk_bf16_f32 v54, v60, v61
	v_cvt_pk_bf16_f32 v55, v62, v63
	v_cvt_pk_bf16_f32 v56, v32, v33
	v_cvt_pk_bf16_f32 v57, v34, v35
	v_cvt_pk_bf16_f32 v58, v36, v37
	v_cvt_pk_bf16_f32 v59, v38, v39
	v_cvt_pk_bf16_f32 v60, v40, v41
	v_cvt_pk_bf16_f32 v61, v42, v43
	v_cvt_pk_bf16_f32 v62, v44, v45
	v_cvt_pk_bf16_f32 v63, v46, v47
	s_waitcnt lgkmcnt(7)
	v_mfma_f32_32x32x16_bf16 v[16:31], v[156:159], v[48:51], v[16:31]
	s_waitcnt lgkmcnt(5)
	v_mfma_f32_32x32x16_bf16 v[0:15], v[152:155], v[48:51], v[0:15]
	s_nop 0
	v_mfma_f32_32x32x16_bf16 v[16:31], v[148:151], v[52:55], v[16:31]
	s_waitcnt lgkmcnt(4)
	v_mfma_f32_32x32x16_bf16 v[0:15], v[144:147], v[52:55], v[0:15]
	s_waitcnt lgkmcnt(3)
	v_mfma_f32_32x32x16_bf16 v[16:31], v[140:143], v[56:59], v[16:31]
	s_waitcnt lgkmcnt(2)
	v_mfma_f32_32x32x16_bf16 v[0:15], v[136:139], v[56:59], v[0:15]
	s_waitcnt lgkmcnt(1)
	s_nop 0
	v_mfma_f32_32x32x16_bf16 v[16:31], v[132:135], v[60:63], v[16:31]
	ds_read_b128 v[36:39], v210 offset:13312
	ds_read_b128 v[132:135], v210 offset:13344
	ds_read_b128 v[136:139], v210 offset:13376
	ds_read_b128 v[140:143], v210 offset:13408
	ds_read_b128 v[144:147], v210 offset:13440
	ds_read_b128 v[148:151], v210 offset:13472
	ds_read_b128 v[40:43], v210 offset:19968
	ds_read_b128 v[152:155], v210 offset:20000
	ds_read_b128 v[156:159], v210 offset:20032
	ds_read_b128 v[234:237], v210 offset:20064
	ds_read_b128 v[238:241], v210 offset:20096
	ds_read_b128 v[242:245], v210 offset:20128
	s_waitcnt lgkmcnt(12)
	v_mfma_f32_32x32x16_bf16 v[0:15], v[128:131], v[60:63], v[0:15]
; DI void phase_attn(const Params& p, int hf, bool skipctx, char* smem, int& rot) {
;     ...
;       const char* sk = smem + buf * STG + half * 64 * KROW; const char* sv = smem + buf * STG + KB_ + half * 128;
;       f32x16 st[2]; st[0] = zero16(); st[1] = zero16();
;       {
;         bf16x8 kf[2][6];
; #pragma unroll
;         for (int kb = 0; kb < 2; ++kb)
; #pragma unroll
;           for (int ks = 0; ks < 6; ++ks) kf[kb][ks] = *(const bf16x8*)(sk + (kb * 32 + r) * KROW + (ks * 16 + h * 8) * 2);
;         __builtin_amdgcn_sched_barrier(0);
; #pragma unroll
;         for (int ks = 0; ks < 6; ++ks)
; #pragma unroll
;           for (int kb = 0; kb < 2; ++kb) st[kb] = MFMA(kf[kb][ks], qf[ks], st[kb]);
;         __builtin_amdgcn_sched_barrier(0);
;       }
;       bf16x8 vf[2][2][2];
; #pragma unroll
;       for (int kb = 0; kb < 2; ++kb)
; #pragma unroll
;         for (int s2 = 0; s2 < 2; ++s2)
; #pragma unroll
;           for (int dvb = 0; dvb < 2; ++dvb) {
;             const char* vp = sv + (dvb * 32 + r) * VROW + (kb * 32 + 16 * s2 + 4 * h) * 2;
;             const s16x4 lo = *(const s16x4*)vp, hi = *(const s16x4*)(vp + 16);
;             vf[kb][s2][dvb] = __builtin_shufflevector(lo, hi, 0, 1, 2, 3, 4, 5, 6, 7);
;           }
;       float mx = st[0][0];
; #pragma unroll
;       for (int i = 0; i < 16; ++i) { mx = fmaxf(mx, st[0][i]); mx = fmaxf(mx, st[1][i]); }
;       if (__any(mx > m_run + 8.f)) {
;         mx = fmaxf(mx, __shfl_xor(mx, 32));
;         const float m_new = fmaxf(m_run, mx);
;         const float alpha = fexp2(m_run - m_new);
;         m_run = m_new;
;         l_run *= alpha;
; #pragma unroll
;         for (int i = 0; i < 16; ++i) { o[0][i] *= alpha; o[1][i] *= alpha; }
;       }
;       float ps = 0.f;
; #pragma unroll
;       for (int kb = 0; kb < 2; ++kb)
; #pragma unroll
;         for (int i = 0; i < 16; ++i) { const float e = fexp2(st[kb][i] - m_run); st[kb][i] = e; ps += e; }
;       l_run += ps;
; #pragma unroll
;       for (int kb = 0; kb < 2; ++kb)
; #pragma unroll
;         for (int s2 = 0; s2 < 2; ++s2) {
;           const bf16x8 pb = pack8(st[kb][8 * s2 + 0], st[kb][8 * s2 + 1], st[kb][8 * s2 + 2], st[kb][8 * s2 + 3], st[kb][8 * s2 + 4], st[kb][8 * s2 + 5], st[kb][8 * s2 + 6], st[kb][8 * s2 + 7]);
; #pragma unroll
;           for (int dvb = 0; dvb < 2; ++dvb) o[dvb] = MFMA(vf[kb][s2][dvb], pb, o[dvb]);
.Lsc0_mj0:
	s_waitcnt lgkmcnt(11)
	v_mfma_f32_32x32x16_bf16 v[48:63], v[36:39], v[64:67], v[176:191]
	s_waitcnt lgkmcnt(5)
	v_mfma_f32_32x32x16_bf16 v[32:47], v[40:43], v[64:67], v[176:191]
	v_mfma_f32_32x32x16_bf16 v[48:63], v[132:135], v[68:71], v[48:63]
	s_waitcnt lgkmcnt(4)
	v_mfma_f32_32x32x16_bf16 v[32:47], v[152:155], v[68:71], v[32:47]
	v_mfma_f32_32x32x16_bf16 v[48:63], v[136:139], v[72:75], v[48:63]
	s_waitcnt lgkmcnt(3)
	v_mfma_f32_32x32x16_bf16 v[32:47], v[156:159], v[72:75], v[32:47]
	v_mfma_f32_32x32x16_bf16 v[48:63], v[140:143], v[88:91], v[48:63]
	s_waitcnt lgkmcnt(2)
	v_mfma_f32_32x32x16_bf16 v[32:47], v[234:237], v[88:91], v[32:47]
	v_mfma_f32_32x32x16_bf16 v[48:63], v[144:147], v[96:99], v[48:63]
	s_waitcnt lgkmcnt(1)
	v_mfma_f32_32x32x16_bf16 v[32:47], v[238:241], v[96:99], v[32:47]
	v_mfma_f32_32x32x16_bf16 v[48:63], v[148:151], v[100:103], v[48:63]
	s_waitcnt lgkmcnt(0)
	v_mfma_f32_32x32x16_bf16 v[32:47], v[242:245], v[100:103], v[32:47]
	s_nop 3
	ds_read_b128 v[156:159], v211 offset:128
	ds_read_b128 v[148:151], v211 offset:160
	ds_read_b128 v[152:155], v211 offset:8832
	ds_read_b128 v[144:147], v211 offset:8864
	ds_read_b128 v[140:143], v211 offset:192
	ds_read_b128 v[136:139], v211 offset:8896
	ds_read_b128 v[128:131], v211 offset:224
	ds_read_b128 v[132:135], v211 offset:8928
	v_exp_f32_e32 v48, v48
	v_exp_f32_e32 v49, v49
	v_exp_f32_e32 v50, v50
	v_exp_f32_e32 v51, v51
	v_exp_f32_e32 v52, v52
	v_exp_f32_e32 v53, v53
	v_exp_f32_e32 v54, v54
	v_exp_f32_e32 v55, v55
	v_exp_f32_e32 v56, v56
	v_exp_f32_e32 v57, v57
	v_exp_f32_e32 v58, v58
	v_exp_f32_e32 v59, v59
	v_exp_f32_e32 v60, v60
	v_exp_f32_e32 v61, v61
	v_exp_f32_e32 v62, v62
	v_exp_f32_e32 v63, v63
	v_exp_f32_e32 v32, v32
	v_exp_f32_e32 v33, v33
	v_exp_f32_e32 v34, v34
	v_exp_f32_e32 v35, v35
	v_exp_f32_e32 v36, v36
	v_exp_f32_e32 v37, v37
	v_exp_f32_e32 v38, v38
	v_exp_f32_e32 v39, v39
	v_exp_f32_e32 v40, v40
	v_exp_f32_e32 v41, v41
	v_exp_f32_e32 v42, v42
	v_exp_f32_e32 v43, v43
	v_exp_f32_e32 v44, v44
	v_exp_f32_e32 v45, v45
	v_exp_f32_e32 v46, v46
	v_exp_f32_e32 v47, v47
	v_add_f32_e32 v195, v48, v49
	v_add_f32_e32 v195, v195, v50
	v_add_f32_e32 v195, v195, v51
	v_add_f32_e32 v195, v195, v52
	v_add_f32_e32 v195, v195, v53
	v_add_f32_e32 v195, v195, v54
	v_add_f32_e32 v195, v195, v55
	v_add_f32_e32 v195, v195, v56
	v_add_f32_e32 v195, v195, v57
	v_add_f32_e32 v195, v195, v58
	v_add_f32_e32 v195, v195, v59
	v_add_f32_e32 v195, v195, v60
	v_add_f32_e32 v195, v195, v61
	v_add_f32_e32 v195, v195, v62
	v_add_f32_e32 v195, v195, v63
	v_add_f32_e32 v195, v195, v32
	v_add_f32_e32 v195, v195, v33
	v_add_f32_e32 v195, v195, v34
	v_add_f32_e32 v195, v195, v35
	v_add_f32_e32 v195, v195, v36
	v_add_f32_e32 v195, v195, v37
	v_add_f32_e32 v195, v195, v38
	v_add_f32_e32 v195, v195, v39
	v_add_f32_e32 v195, v195, v40
	v_add_f32_e32 v195, v195, v41
	v_add_f32_e32 v195, v195, v42
	v_add_f32_e32 v195, v195, v43
	v_add_f32_e32 v195, v195, v44
	v_add_f32_e32 v195, v195, v45
	v_add_f32_e32 v195, v195, v46
	v_add_f32_e32 v195, v195, v47
	v_cmp_nle_f32_e32 vcc, v195, v167
	s_cbranch_vccnz .Lsc0_fb1
	v_add_f32_e32 v213, v213, v195
	v_cvt_pk_bf16_f32 v48, v48, v49
	v_cvt_pk_bf16_f32 v49, v50, v51
	v_cvt_pk_bf16_f32 v50, v52, v53
	v_cvt_pk_bf16_f32 v51, v54, v55
	v_cvt_pk_bf16_f32 v52, v56, v57
	v_cvt_pk_bf16_f32 v53, v58, v59
	v_cvt_pk_bf16_f32 v54, v60, v61
	v_cvt_pk_bf16_f32 v55, v62, v63
	v_cvt_pk_bf16_f32 v56, v32, v33
	v_cvt_pk_bf16_f32 v57, v34, v35
	v_cvt_pk_bf16_f32 v58, v36, v37
	v_cvt_pk_bf16_f32 v59, v38, v39
	v_cvt_pk_bf16_f32 v60, v40, v41
	v_cvt_pk_bf16_f32 v61, v42, v43
	v_cvt_pk_bf16_f32 v62, v44, v45
	v_cvt_pk_bf16_f32 v63, v46, v47
	s_waitcnt lgkmcnt(7)
	s_nop 0
	v_mfma_f32_32x32x16_bf16 v[16:31], v[156:159], v[48:51], v[16:31]
	s_waitcnt lgkmcnt(5)
	v_mfma_f32_32x32x16_bf16 v[0:15], v[152:155], v[48:51], v[0:15]
	s_nop 1
	v_mfma_f32_32x32x16_bf16 v[16:31], v[148:151], v[52:55], v[16:31]
	s_waitcnt lgkmcnt(4)
	v_mfma_f32_32x32x16_bf16 v[0:15], v[144:147], v[52:55], v[0:15]
	s_waitcnt lgkmcnt(3)
	s_nop 0
	v_mfma_f32_32x32x16_bf16 v[16:31], v[140:143], v[56:59], v[16:31]
	s_waitcnt lgkmcnt(2)
	v_mfma_f32_32x32x16_bf16 v[0:15], v[136:139], v[56:59], v[0:15]
	s_add_i32 s4, s4, 3
	s_cmp_ge_u32 s4, s13
	s_waitcnt lgkmcnt(1)
	v_mfma_f32_32x32x16_bf16 v[16:31], v[128:131], v[60:63], v[16:31]
	s_waitcnt vmcnt(1)
	ds_write_b128 v194, v[112:115] offset:44032
	ds_write_b128 v204, v[108:111] offset:44032
	ds_write_b128 v206, v[116:119] offset:44032
	ds_write_b64 v208, v[120:121] offset:44032
	ds_write_b64 v208, v[122:123] offset:44048
	s_waitcnt vmcnt(0)
	ds_write_b64 v208, v[124:125] offset:52736
	ds_write_b64 v208, v[126:127] offset:52752
	s_waitcnt lgkmcnt(0)
	s_barrier
	v_mfma_f32_32x32x16_bf16 v[0:15], v[132:135], v[60:63], v[0:15]
	s_cbranch_scc1 .LBB0_803
	v_add_u32_e32 v200, 0x6000, v174
	v_add_u32_e32 v201, 0x6000, v172
	v_add_u32_e32 v202, 0x6000, v170
	global_load_dwordx4 v[112:115], v200, s[94:95]
	global_load_dwordx4 v[108:111], v201, s[94:95]
	global_load_dwordx4 v[116:119], v202, s[94:95]
	global_load_dwordx4 v[120:123], v166, s[94:95]
	global_load_dwordx4 v[124:127], v168, s[94:95]
.LBB0_803:
	ds_read_b128 v[32:35], v210 offset:44032
	ds_read_b128 v[128:131], v210 offset:44064
	ds_read_b128 v[132:135], v210 offset:44096
	ds_read_b128 v[136:139], v210 offset:44128
	ds_read_b128 v[140:143], v210 offset:44160
	ds_read_b128 v[144:147], v210 offset:44192
	ds_read_b128 v[36:39], v210 offset:50688
	ds_read_b128 v[148:151], v210 offset:50720
	ds_read_b128 v[152:155], v210 offset:50752
	ds_read_b128 v[156:159], v210 offset:50784
	ds_read_b128 v[214:217], v210 offset:50816
	ds_read_b128 v[234:237], v210 offset:50848
; DI void phase_attn(const Params& p, int hf, bool skipctx, char* smem, int& rot) {
;     ...
;       const char* sk = smem + buf * STG + half * 64 * KROW; const char* sv = smem + buf * STG + KB_ + half * 128;
;       f32x16 st[2]; st[0] = zero16(); st[1] = zero16();
;       {
;         bf16x8 kf[2][6];
; #pragma unroll
;         for (int kb = 0; kb < 2; ++kb)
; #pragma unroll
;           for (int ks = 0; ks < 6; ++ks) kf[kb][ks] = *(const bf16x8*)(sk + (kb * 32 + r) * KROW + (ks * 16 + h * 8) * 2);
;         __builtin_amdgcn_sched_barrier(0);
; #pragma unroll
;         for (int ks = 0; ks < 6; ++ks)
; #pragma unroll
;           for (int kb = 0; kb < 2; ++kb) st[kb] = MFMA(kf[kb][ks], qf[ks], st[kb]);
;         __builtin_amdgcn_sched_barrier(0);
;       }
;       bf16x8 vf[2][2][2];
; #pragma unroll
;       for (int kb = 0; kb < 2; ++kb)
; #pragma unroll
;         for (int s2 = 0; s2 < 2; ++s2)
; #pragma unroll
;           for (int dvb = 0; dvb < 2; ++dvb) {
;             const char* vp = sv + (dvb * 32 + r) * VROW + (kb * 32 + 16 * s2 + 4 * h) * 2;
;             const s16x4 lo = *(const s16x4*)vp, hi = *(const s16x4*)(vp + 16);
;             vf[kb][s2][dvb] = __builtin_shufflevector(lo, hi, 0, 1, 2, 3, 4, 5, 6, 7);
;           }
;       float mx = st[0][0];
; #pragma unroll
;       for (int i = 0; i < 16; ++i) { mx = fmaxf(mx, st[0][i]); mx = fmaxf(mx, st[1][i]); }
;       if (__any(mx > m_run + 8.f)) {
;         mx = fmaxf(mx, __shfl_xor(mx, 32));
;         const float m_new = fmaxf(m_run, mx);
;         const float alpha = fexp2(m_run - m_new);
;         m_run = m_new;
;         l_run *= alpha;
; #pragma unroll
;         for (int i = 0; i < 16; ++i) { o[0][i] *= alpha; o[1][i] *= alpha; }
;       }
;       float ps = 0.f;
; #pragma unroll
;       for (int kb = 0; kb < 2; ++kb)
; #pragma unroll
;         for (int i = 0; i < 16; ++i) { const float e = fexp2(st[kb][i] - m_run); st[kb][i] = e; ps += e; }
;       l_run += ps;
; #pragma unroll
;       for (int kb = 0; kb < 2; ++kb)
; #pragma unroll
;         for (int s2 = 0; s2 < 2; ++s2) {
;           const bf16x8 pb = pack8(st[kb][8 * s2 + 0], st[kb][8 * s2 + 1], st[kb][8 * s2 + 2], st[kb][8 * s2 + 3], st[kb][8 * s2 + 4], st[kb][8 * s2 + 5], st[kb][8 * s2 + 6], st[kb][8 * s2 + 7]);
; #pragma unroll
;           for (int dvb = 0; dvb < 2; ++dvb) o[dvb] = MFMA(vf[kb][s2][dvb], pb, o[dvb]);
.Lsc0_mj1:
	s_waitcnt lgkmcnt(11)
	v_mfma_f32_32x32x16_bf16 v[48:63], v[32:35], v[64:67], v[176:191]
	s_waitcnt lgkmcnt(5)
	v_mfma_f32_32x32x16_bf16 v[32:47], v[36:39], v[64:67], v[176:191]
	v_mfma_f32_32x32x16_bf16 v[48:63], v[128:131], v[68:71], v[48:63]
	s_waitcnt lgkmcnt(4)
	v_mfma_f32_32x32x16_bf16 v[32:47], v[148:151], v[68:71], v[32:47]
	v_mfma_f32_32x32x16_bf16 v[48:63], v[132:135], v[72:75], v[48:63]
	s_waitcnt lgkmcnt(3)
	v_mfma_f32_32x32x16_bf16 v[32:47], v[152:155], v[72:75], v[32:47]
	v_mfma_f32_32x32x16_bf16 v[48:63], v[136:139], v[88:91], v[48:63]
	s_waitcnt lgkmcnt(2)
	v_mfma_f32_32x32x16_bf16 v[32:47], v[156:159], v[88:91], v[32:47]
	v_mfma_f32_32x32x16_bf16 v[48:63], v[140:143], v[96:99], v[48:63]
	s_waitcnt lgkmcnt(1)
	v_mfma_f32_32x32x16_bf16 v[32:47], v[214:217], v[96:99], v[32:47]
	v_mfma_f32_32x32x16_bf16 v[48:63], v[144:147], v[100:103], v[48:63]
	s_waitcnt lgkmcnt(0)
	v_mfma_f32_32x32x16_bf16 v[32:47], v[234:237], v[100:103], v[32:47]
	s_nop 3
	ds_read_b128 v[152:155], v211 offset:52736
	ds_read_b128 v[156:159], v211 offset:44032
	ds_read_b128 v[148:151], v211 offset:44064
	ds_read_b128 v[144:147], v211 offset:52768
	ds_read_b128 v[140:143], v211 offset:44096
	ds_read_b128 v[136:139], v211 offset:52800
	ds_read_b128 v[132:135], v211 offset:44128
	ds_read_b128 v[128:131], v211 offset:52832
	v_exp_f32_e32 v48, v48
	v_exp_f32_e32 v49, v49
	v_exp_f32_e32 v50, v50
	v_exp_f32_e32 v51, v51
	v_exp_f32_e32 v52, v52
	v_exp_f32_e32 v53, v53
	v_exp_f32_e32 v54, v54
	v_exp_f32_e32 v55, v55
	v_exp_f32_e32 v56, v56
	v_exp_f32_e32 v57, v57
	v_exp_f32_e32 v58, v58
	v_exp_f32_e32 v59, v59
	v_exp_f32_e32 v60, v60
	v_exp_f32_e32 v61, v61
	v_exp_f32_e32 v62, v62
	v_exp_f32_e32 v63, v63
	v_exp_f32_e32 v32, v32
	v_exp_f32_e32 v33, v33
	v_exp_f32_e32 v34, v34
	v_exp_f32_e32 v35, v35
	v_exp_f32_e32 v36, v36
	v_exp_f32_e32 v37, v37
	v_exp_f32_e32 v38, v38
	v_exp_f32_e32 v39, v39
	v_exp_f32_e32 v40, v40
	v_exp_f32_e32 v41, v41
	v_exp_f32_e32 v42, v42
	v_exp_f32_e32 v43, v43
	v_exp_f32_e32 v44, v44
	v_exp_f32_e32 v45, v45
	v_exp_f32_e32 v46, v46
	v_exp_f32_e32 v47, v47
	v_add_f32_e32 v195, v48, v49
	v_add_f32_e32 v195, v195, v50
	v_add_f32_e32 v195, v195, v51
	v_add_f32_e32 v195, v195, v52
	v_add_f32_e32 v195, v195, v53
	v_add_f32_e32 v195, v195, v54
	v_add_f32_e32 v195, v195, v55
	v_add_f32_e32 v195, v195, v56
	v_add_f32_e32 v195, v195, v57
	v_add_f32_e32 v195, v195, v58
	v_add_f32_e32 v195, v195, v59
	v_add_f32_e32 v195, v195, v60
	v_add_f32_e32 v195, v195, v61
	v_add_f32_e32 v195, v195, v62
	v_add_f32_e32 v195, v195, v63
	v_add_f32_e32 v195, v195, v32
	v_add_f32_e32 v195, v195, v33
	v_add_f32_e32 v195, v195, v34
	v_add_f32_e32 v195, v195, v35
	v_add_f32_e32 v195, v195, v36
	v_add_f32_e32 v195, v195, v37
	v_add_f32_e32 v195, v195, v38
	v_add_f32_e32 v195, v195, v39
	v_add_f32_e32 v195, v195, v40
	v_add_f32_e32 v195, v195, v41
	v_add_f32_e32 v195, v195, v42
	v_add_f32_e32 v195, v195, v43
	v_add_f32_e32 v195, v195, v44
	v_add_f32_e32 v195, v195, v45
	v_add_f32_e32 v195, v195, v46
	v_add_f32_e32 v195, v195, v47
	v_cmp_nle_f32_e32 vcc, v195, v167
	s_cbranch_vccnz .Lsc0_fb2
	v_add_f32_e32 v213, v213, v195
	v_cvt_pk_bf16_f32 v48, v48, v49
	v_cvt_pk_bf16_f32 v49, v50, v51
	v_cvt_pk_bf16_f32 v50, v52, v53
	v_cvt_pk_bf16_f32 v51, v54, v55
	v_cvt_pk_bf16_f32 v52, v56, v57
	v_cvt_pk_bf16_f32 v53, v58, v59
	v_cvt_pk_bf16_f32 v54, v60, v61
	v_cvt_pk_bf16_f32 v55, v62, v63
	v_cvt_pk_bf16_f32 v56, v32, v33
	v_cvt_pk_bf16_f32 v57, v34, v35
	v_cvt_pk_bf16_f32 v58, v36, v37
	v_cvt_pk_bf16_f32 v59, v38, v39
	v_cvt_pk_bf16_f32 v60, v40, v41
	v_cvt_pk_bf16_f32 v61, v42, v43
	v_cvt_pk_bf16_f32 v62, v44, v45
	v_cvt_pk_bf16_f32 v63, v46, v47
	s_waitcnt lgkmcnt(6)
	v_mfma_f32_32x32x16_bf16 v[16:31], v[156:159], v[48:51], v[16:31]
	v_mfma_f32_32x32x16_bf16 v[0:15], v[152:155], v[48:51], v[0:15]
	s_waitcnt lgkmcnt(5)
	v_mfma_f32_32x32x16_bf16 v[16:31], v[148:151], v[52:55], v[16:31]
	s_waitcnt lgkmcnt(4)
	v_mfma_f32_32x32x16_bf16 v[0:15], v[144:147], v[52:55], v[0:15]
	s_waitcnt lgkmcnt(3)
	v_mfma_f32_32x32x16_bf16 v[16:31], v[140:143], v[56:59], v[16:31]
	s_waitcnt lgkmcnt(2)
	v_mfma_f32_32x32x16_bf16 v[0:15], v[136:139], v[56:59], v[0:15]
	s_waitcnt lgkmcnt(1)
	s_nop 0
	v_mfma_f32_32x32x16_bf16 v[16:31], v[132:135], v[60:63], v[16:31]
	ds_read_b128 v[36:39], v210 offset:57344
	ds_read_b128 v[132:135], v210 offset:57376
	ds_read_b128 v[136:139], v210 offset:57408
	ds_read_b128 v[140:143], v210 offset:57440
	ds_read_b128 v[144:147], v210 offset:57472
	ds_read_b128 v[148:151], v210 offset:57504
	ds_read_b128 v[40:43], v210 offset:64000
	ds_read_b128 v[152:155], v210 offset:64032
	ds_read_b128 v[156:159], v210 offset:64064
	ds_read_b128 v[216:219], v210 offset:64096
	ds_read_b128 v[234:237], v210 offset:64128
	ds_read_b128 v[238:241], v210 offset:64160
	s_waitcnt lgkmcnt(12)
	v_mfma_f32_32x32x16_bf16 v[0:15], v[128:131], v[60:63], v[0:15]
; DI void phase_attn(const Params& p, int hf, bool skipctx, char* smem, int& rot) {
;     ...
;       const char* sk = smem + buf * STG + half * 64 * KROW; const char* sv = smem + buf * STG + KB_ + half * 128;
;       f32x16 st[2]; st[0] = zero16(); st[1] = zero16();
;       {
;         bf16x8 kf[2][6];
; #pragma unroll
;         for (int kb = 0; kb < 2; ++kb)
; #pragma unroll
;           for (int ks = 0; ks < 6; ++ks) kf[kb][ks] = *(const bf16x8*)(sk + (kb * 32 + r) * KROW + (ks * 16 + h * 8) * 2);
;         __builtin_amdgcn_sched_barrier(0);
; #pragma unroll
;         for (int ks = 0; ks < 6; ++ks)
; #pragma unroll
;           for (int kb = 0; kb < 2; ++kb) st[kb] = MFMA(kf[kb][ks], qf[ks], st[kb]);
;         __builtin_amdgcn_sched_barrier(0);
;       }
;       bf16x8 vf[2][2][2];
; #pragma unroll
;       for (int kb = 0; kb < 2; ++kb)
; #pragma unroll
;         for (int s2 = 0; s2 < 2; ++s2)
; #pragma unroll
;           for (int dvb = 0; dvb < 2; ++dvb) {
;             const char* vp = sv + (dvb * 32 + r) * VROW + (kb * 32 + 16 * s2 + 4 * h) * 2;
;             const s16x4 lo = *(const s16x4*)vp, hi = *(const s16x4*)(vp + 16);
;             vf[kb][s2][dvb] = __builtin_shufflevector(lo, hi, 0, 1, 2, 3, 4, 5, 6, 7);
;           }
;       float mx = st[0][0];
; #pragma unroll
;       for (int i = 0; i < 16; ++i) { mx = fmaxf(mx, st[0][i]); mx = fmaxf(mx, st[1][i]); }
;       if (__any(mx > m_run + 8.f)) {
;         mx = fmaxf(mx, __shfl_xor(mx, 32));
;         const float m_new = fmaxf(m_run, mx);
;         const float alpha = fexp2(m_run - m_new);
;         m_run = m_new;
;         l_run *= alpha;
; #pragma unroll
;         for (int i = 0; i < 16; ++i) { o[0][i] *= alpha; o[1][i] *= alpha; }
;       }
;       float ps = 0.f;
; #pragma unroll
;       for (int kb = 0; kb < 2; ++kb)
; #pragma unroll
;         for (int i = 0; i < 16; ++i) { const float e = fexp2(st[kb][i] - m_run); st[kb][i] = e; ps += e; }
;       l_run += ps;
; #pragma unroll
;       for (int kb = 0; kb < 2; ++kb)
; #pragma unroll
;         for (int s2 = 0; s2 < 2; ++s2) {
;           const bf16x8 pb = pack8(st[kb][8 * s2 + 0], st[kb][8 * s2 + 1], st[kb][8 * s2 + 2], st[kb][8 * s2 + 3], st[kb][8 * s2 + 4], st[kb][8 * s2 + 5], st[kb][8 * s2 + 6], st[kb][8 * s2 + 7]);
; #pragma unroll
;           for (int dvb = 0; dvb < 2; ++dvb) o[dvb] = MFMA(vf[kb][s2][dvb], pb, o[dvb]);
.Lsc0_mj2:
	s_waitcnt lgkmcnt(11)
	v_mfma_f32_32x32x16_bf16 v[48:63], v[36:39], v[64:67], v[176:191]
	s_waitcnt lgkmcnt(5)
	v_mfma_f32_32x32x16_bf16 v[32:47], v[40:43], v[64:67], v[176:191]
	v_mfma_f32_32x32x16_bf16 v[48:63], v[132:135], v[68:71], v[48:63]
	s_waitcnt lgkmcnt(4)
	v_mfma_f32_32x32x16_bf16 v[32:47], v[152:155], v[68:71], v[32:47]
	v_mfma_f32_32x32x16_bf16 v[48:63], v[136:139], v[72:75], v[48:63]
	s_waitcnt lgkmcnt(3)
	v_mfma_f32_32x32x16_bf16 v[32:47], v[156:159], v[72:75], v[32:47]
	v_mfma_f32_32x32x16_bf16 v[48:63], v[140:143], v[88:91], v[48:63]
	s_waitcnt lgkmcnt(2)
	v_mfma_f32_32x32x16_bf16 v[32:47], v[216:219], v[88:91], v[32:47]
	v_mfma_f32_32x32x16_bf16 v[48:63], v[144:147], v[96:99], v[48:63]
	s_waitcnt lgkmcnt(1)
	v_mfma_f32_32x32x16_bf16 v[32:47], v[234:237], v[96:99], v[32:47]
	v_mfma_f32_32x32x16_bf16 v[48:63], v[148:151], v[100:103], v[48:63]
	s_waitcnt lgkmcnt(0)
	v_mfma_f32_32x32x16_bf16 v[32:47], v[238:241], v[100:103], v[32:47]
	s_nop 3
	ds_read_b128 v[152:155], v211 offset:52864
	ds_read_b128 v[156:159], v211 offset:44160
	ds_read_b128 v[148:151], v211 offset:44192
	ds_read_b128 v[144:147], v211 offset:52896
	ds_read_b128 v[140:143], v211 offset:44224
	ds_read_b128 v[136:139], v211 offset:52928
	ds_read_b128 v[132:135], v211 offset:44256
	ds_read_b128 v[128:131], v211 offset:52960
	v_exp_f32_e32 v48, v48
	v_exp_f32_e32 v49, v49
	v_exp_f32_e32 v50, v50
	v_exp_f32_e32 v51, v51
	v_exp_f32_e32 v52, v52
	v_exp_f32_e32 v53, v53
	v_exp_f32_e32 v54, v54
	v_exp_f32_e32 v55, v55
	v_exp_f32_e32 v56, v56
	v_exp_f32_e32 v57, v57
	v_exp_f32_e32 v58, v58
	v_exp_f32_e32 v59, v59
	v_exp_f32_e32 v60, v60
	v_exp_f32_e32 v61, v61
	v_exp_f32_e32 v62, v62
	v_exp_f32_e32 v63, v63
	v_exp_f32_e32 v32, v32
	v_exp_f32_e32 v33, v33
	v_exp_f32_e32 v34, v34
	v_exp_f32_e32 v35, v35
	v_exp_f32_e32 v36, v36
	v_exp_f32_e32 v37, v37
	v_exp_f32_e32 v38, v38
	v_exp_f32_e32 v39, v39
	v_exp_f32_e32 v40, v40
	v_exp_f32_e32 v41, v41
	v_exp_f32_e32 v42, v42
	v_exp_f32_e32 v43, v43
	v_exp_f32_e32 v44, v44
	v_exp_f32_e32 v45, v45
	v_exp_f32_e32 v46, v46
	v_exp_f32_e32 v47, v47
	v_add_f32_e32 v195, v48, v49
	v_add_f32_e32 v195, v195, v50
	v_add_f32_e32 v195, v195, v51
	v_add_f32_e32 v195, v195, v52
	v_add_f32_e32 v195, v195, v53
	v_add_f32_e32 v195, v195, v54
	v_add_f32_e32 v195, v195, v55
	v_add_f32_e32 v195, v195, v56
	v_add_f32_e32 v195, v195, v57
	v_add_f32_e32 v195, v195, v58
	v_add_f32_e32 v195, v195, v59
	v_add_f32_e32 v195, v195, v60
	v_add_f32_e32 v195, v195, v61
	v_add_f32_e32 v195, v195, v62
	v_add_f32_e32 v195, v195, v63
	v_add_f32_e32 v195, v195, v32
	v_add_f32_e32 v195, v195, v33
	v_add_f32_e32 v195, v195, v34
	v_add_f32_e32 v195, v195, v35
	v_add_f32_e32 v195, v195, v36
	v_add_f32_e32 v195, v195, v37
	v_add_f32_e32 v195, v195, v38
	v_add_f32_e32 v195, v195, v39
	v_add_f32_e32 v195, v195, v40
	v_add_f32_e32 v195, v195, v41
	v_add_f32_e32 v195, v195, v42
	v_add_f32_e32 v195, v195, v43
	v_add_f32_e32 v195, v195, v44
	v_add_f32_e32 v195, v195, v45
	v_add_f32_e32 v195, v195, v46
	v_add_f32_e32 v195, v195, v47
	v_cmp_nle_f32_e32 vcc, v195, v167
	s_cbranch_vccnz .Lsc0_fb3
	v_add_f32_e32 v213, v213, v195
	v_cvt_pk_bf16_f32 v48, v48, v49
	v_cvt_pk_bf16_f32 v49, v50, v51
	v_cvt_pk_bf16_f32 v50, v52, v53
	v_cvt_pk_bf16_f32 v51, v54, v55
	v_cvt_pk_bf16_f32 v52, v56, v57
	v_cvt_pk_bf16_f32 v53, v58, v59
	v_cvt_pk_bf16_f32 v54, v60, v61
	v_cvt_pk_bf16_f32 v55, v62, v63
	v_cvt_pk_bf16_f32 v56, v32, v33
	v_cvt_pk_bf16_f32 v57, v34, v35
	v_cvt_pk_bf16_f32 v58, v36, v37
	v_cvt_pk_bf16_f32 v59, v38, v39
	v_cvt_pk_bf16_f32 v60, v40, v41
	v_cvt_pk_bf16_f32 v61, v42, v43
	v_cvt_pk_bf16_f32 v62, v44, v45
	v_cvt_pk_bf16_f32 v63, v46, v47
	s_waitcnt lgkmcnt(6)
	s_nop 0
	v_mfma_f32_32x32x16_bf16 v[16:31], v[156:159], v[48:51], v[16:31]
	v_mfma_f32_32x32x16_bf16 v[0:15], v[152:155], v[48:51], v[0:15]
	s_waitcnt lgkmcnt(5)
	s_nop 0
	v_mfma_f32_32x32x16_bf16 v[16:31], v[148:151], v[52:55], v[16:31]
	s_waitcnt lgkmcnt(4)
	v_mfma_f32_32x32x16_bf16 v[0:15], v[144:147], v[52:55], v[0:15]
	s_waitcnt lgkmcnt(3)
	s_nop 0
	v_mfma_f32_32x32x16_bf16 v[16:31], v[140:143], v[56:59], v[16:31]
	s_waitcnt lgkmcnt(2)
	v_mfma_f32_32x32x16_bf16 v[0:15], v[136:139], v[56:59], v[0:15]
	s_andn2_b64 vcc, exec, s[36:37]
	s_waitcnt lgkmcnt(1)
	v_mfma_f32_32x32x16_bf16 v[16:31], v[132:135], v[60:63], v[16:31]
	s_waitcnt lgkmcnt(0)
	v_mfma_f32_32x32x16_bf16 v[0:15], v[128:131], v[60:63], v[0:15]
	s_cbranch_vccnz .LBB0_809
	ds_write_b128 v194, v[76:79]
	ds_write_b128 v204, v[80:83]
	ds_write_b128 v206, v[84:87]
	ds_write_b64 v208, v[92:93] offset:0
	ds_write_b64 v208, v[94:95] offset:16
	ds_write_b64 v208, v[104:105] offset:8704
	ds_write_b64 v208, v[106:107] offset:8720
.LBB0_809:
	v_add_u32_e32 v166, s24, v166
	v_add_u32_e32 v168, s24, v168
	v_add_u32_e32 v170, s30, v170
	v_add_u32_e32 v172, s30, v172
	v_add_u32_e32 v174, s30, v174
	s_and_b64 vcc, exec, s[26:27]
	s_waitcnt lgkmcnt(0)
	s_barrier
	s_cbranch_vccnz .LBB0_770
	s_mov_b32 s4, s15
	s_branch .LBB0_795
; #define MFMA(a, b, c) __builtin_amdgcn_mfma_f32_32x32x16_bf16((a), (b), (c), 0, 0, 0)
; DI float fexp2(float x) { return __builtin_amdgcn_exp2f(x); }
; DI f32x16 zero16() { f32x16 z; for (int i = 0; i < 16; ++i) z[i] = 0.f; return z; }
; DI void phase_attn(const Params& p, int hf, bool skipctx, char* smem, int& rot) {
;     ...
;       const char* sk = smem + buf * STG + half * 64 * KROW; const char* sv = smem + buf * STG + KB_ + half * 128;
;       f32x16 st[2]; st[0] = zero16(); st[1] = zero16();
;       {
;         bf16x8 kf[2][6];
; #pragma unroll
;         for (int kb = 0; kb < 2; ++kb)
; #pragma unroll
;           for (int ks = 0; ks < 6; ++ks) kf[kb][ks] = *(const bf16x8*)(sk + (kb * 32 + r) * KROW + (ks * 16 + h * 8) * 2);
;         __builtin_amdgcn_sched_barrier(0);
; #pragma unroll
;         for (int ks = 0; ks < 6; ++ks)
; #pragma unroll
;           for (int kb = 0; kb < 2; ++kb) st[kb] = MFMA(kf[kb][ks], qf[ks], st[kb]);
;         __builtin_amdgcn_sched_barrier(0);
;       }
;       bf16x8 vf[2][2][2];
; #pragma unroll
;       for (int kb = 0; kb < 2; ++kb)
; #pragma unroll
;         for (int s2 = 0; s2 < 2; ++s2)
; #pragma unroll
;           for (int dvb = 0; dvb < 2; ++dvb) {
;             const char* vp = sv + (dvb * 32 + r) * VROW + (kb * 32 + 16 * s2 + 4 * h) * 2;
;             const s16x4 lo = *(const s16x4*)vp, hi = *(const s16x4*)(vp + 16);
;             vf[kb][s2][dvb] = __builtin_shufflevector(lo, hi, 0, 1, 2, 3, 4, 5, 6, 7);
;           }
;       float mx = st[0][0];
; #pragma unroll
;       for (int i = 0; i < 16; ++i) { mx = fmaxf(mx, st[0][i]); mx = fmaxf(mx, st[1][i]); }
;       if (__any(mx > m_run + 8.f)) {
;         mx = fmaxf(mx, __shfl_xor(mx, 32));
;         const float m_new = fmaxf(m_run, mx);
;         const float alpha = fexp2(m_run - m_new);
;         m_run = m_new;
;         l_run *= alpha;
; #pragma unroll
;         for (int i = 0; i < 16; ++i) { o[0][i] *= alpha; o[1][i] *= alpha; }
;       }
.Lsc0_fb0:
	ds_read_b128 v[32:35], v210
	ds_read_b128 v[128:131], v210 offset:32
	ds_read_b128 v[132:135], v210 offset:64
	ds_read_b128 v[136:139], v210 offset:96
	ds_read_b128 v[140:143], v210 offset:128
	ds_read_b128 v[144:147], v210 offset:160
	ds_read_b128 v[36:39], v210 offset:6656
	ds_read_b128 v[148:151], v210 offset:6688
	ds_read_b128 v[152:155], v210 offset:6720
	ds_read_b128 v[156:159], v210 offset:6752
	ds_read_b128 v[214:217], v210 offset:6784
	ds_read_b128 v[234:237], v210 offset:6816
	s_waitcnt lgkmcnt(0)
	s_waitcnt lgkmcnt(11)
	v_mfma_f32_32x32x16_bf16 v[48:63], v[32:35], v[64:67], v[176:191]
	s_waitcnt lgkmcnt(5)
	v_mfma_f32_32x32x16_bf16 v[32:47], v[36:39], v[64:67], v[176:191]
	v_mfma_f32_32x32x16_bf16 v[48:63], v[128:131], v[68:71], v[48:63]
	s_waitcnt lgkmcnt(4)
	v_mfma_f32_32x32x16_bf16 v[32:47], v[148:151], v[68:71], v[32:47]
	v_mfma_f32_32x32x16_bf16 v[48:63], v[132:135], v[72:75], v[48:63]
	s_waitcnt lgkmcnt(3)
	v_mfma_f32_32x32x16_bf16 v[32:47], v[152:155], v[72:75], v[32:47]
	v_mfma_f32_32x32x16_bf16 v[48:63], v[136:139], v[88:91], v[48:63]
	s_waitcnt lgkmcnt(2)
	v_mfma_f32_32x32x16_bf16 v[32:47], v[156:159], v[88:91], v[32:47]
	v_mfma_f32_32x32x16_bf16 v[48:63], v[140:143], v[96:99], v[48:63]
	s_waitcnt lgkmcnt(1)
	v_mfma_f32_32x32x16_bf16 v[32:47], v[214:217], v[96:99], v[32:47]
	v_mfma_f32_32x32x16_bf16 v[48:63], v[144:147], v[100:103], v[48:63]
	s_waitcnt lgkmcnt(0)
	v_mfma_f32_32x32x16_bf16 v[32:47], v[234:237], v[100:103], v[32:47]
	s_nop 3
	ds_read_b128 v[156:159], v211 offset:0
	ds_read_b128 v[148:151], v211 offset:32
	ds_read_b128 v[152:155], v211 offset:8704
	ds_read_b128 v[144:147], v211 offset:8736
	ds_read_b128 v[140:143], v211 offset:64
	ds_read_b128 v[136:139], v211 offset:8768
	ds_read_b128 v[132:135], v211 offset:96
	ds_read_b128 v[128:131], v211 offset:8800
	v_max3_f32 v195, v32, v48, v49
	v_max_f32_e32 v195, v195, v33
	v_max3_f32 v195, v195, v50, v34
	v_max3_f32 v195, v195, v51, v35
	v_max3_f32 v195, v195, v52, v36
	v_max3_f32 v195, v195, v53, v37
	v_max3_f32 v195, v195, v54, v38
	v_max3_f32 v195, v195, v55, v39
	v_max3_f32 v195, v195, v56, v40
	v_max3_f32 v195, v195, v57, v41
	v_max3_f32 v195, v195, v58, v42
	v_max3_f32 v195, v195, v59, v43
	v_max3_f32 v195, v195, v60, v44
	v_max3_f32 v195, v195, v61, v45
	v_max3_f32 v195, v195, v62, v46
	v_max3_f32 v217, v195, v63, v47
	v_cmp_gt_f32_e32 vcc, v217, v220
	s_cbranch_vccz .Lsc0_c0_LBB0_799
	v_sub_f32_e32 v217, v217, v176
	v_cmp_lt_i32_e32 vcc, v224, v207
	s_nop 1
	v_cndmask_b32_e32 v195, v205, v224, vcc
	v_lshlrev_b32_e32 v195, 2, v195
	ds_bpermute_b32 v195, v195, v217
	s_waitcnt lgkmcnt(0)
	v_max3_f32 v195, v212, v217, v195
	v_sub_f32_e32 v200, v212, v195
	v_exp_f32_e32 v200, v200
	v_mov_b32_e32 v212, v195
	v_mul_f32_e32 v213, v213, v200
	v_pk_mul_f32 v[30:31], v[30:31], v[200:201] op_sel_hi:[1,0]
	v_pk_mul_f32 v[28:29], v[28:29], v[200:201] op_sel_hi:[1,0]
	v_pk_mul_f32 v[26:27], v[26:27], v[200:201] op_sel_hi:[1,0]
	v_pk_mul_f32 v[24:25], v[24:25], v[200:201] op_sel_hi:[1,0]
	v_pk_mul_f32 v[22:23], v[22:23], v[200:201] op_sel_hi:[1,0]
	v_pk_mul_f32 v[20:21], v[20:21], v[200:201] op_sel_hi:[1,0]
	v_pk_mul_f32 v[18:19], v[18:19], v[200:201] op_sel_hi:[1,0]
	v_pk_mul_f32 v[16:17], v[16:17], v[200:201] op_sel_hi:[1,0]
	v_pk_mul_f32 v[14:15], v[14:15], v[200:201] op_sel_hi:[1,0]
	v_pk_mul_f32 v[12:13], v[12:13], v[200:201] op_sel_hi:[1,0]
	v_pk_mul_f32 v[10:11], v[10:11], v[200:201] op_sel_hi:[1,0]
	v_pk_mul_f32 v[8:9], v[8:9], v[200:201] op_sel_hi:[1,0]
	v_pk_mul_f32 v[6:7], v[6:7], v[200:201] op_sel_hi:[1,0]
	v_pk_mul_f32 v[4:5], v[4:5], v[200:201] op_sel_hi:[1,0]
	v_pk_mul_f32 v[2:3], v[2:3], v[200:201] op_sel_hi:[1,0]
	v_pk_mul_f32 v[0:1], v[0:1], v[200:201] op_sel_hi:[1,0]
	v_add_f32_e32 v202, v195, v176
	v_sub_f32_e32 v32, v32, v202
	v_sub_f32_e32 v33, v33, v202
	v_sub_f32_e32 v34, v34, v202
	v_sub_f32_e32 v35, v35, v202
	v_sub_f32_e32 v36, v36, v202
	v_sub_f32_e32 v37, v37, v202
	v_sub_f32_e32 v38, v38, v202
	v_sub_f32_e32 v39, v39, v202
	v_sub_f32_e32 v40, v40, v202
	v_sub_f32_e32 v41, v41, v202
	v_sub_f32_e32 v42, v42, v202
	v_sub_f32_e32 v43, v43, v202
	v_sub_f32_e32 v44, v44, v202
	v_sub_f32_e32 v45, v45, v202
	v_sub_f32_e32 v46, v46, v202
	v_sub_f32_e32 v47, v47, v202
	v_sub_f32_e32 v48, v48, v202
	v_sub_f32_e32 v49, v49, v202
	v_sub_f32_e32 v50, v50, v202
	v_sub_f32_e32 v51, v51, v202
	v_sub_f32_e32 v52, v52, v202
	v_sub_f32_e32 v53, v53, v202
	v_sub_f32_e32 v54, v54, v202
	v_sub_f32_e32 v55, v55, v202
	v_sub_f32_e32 v56, v56, v202
	v_sub_f32_e32 v57, v57, v202
	v_sub_f32_e32 v58, v58, v202
	v_sub_f32_e32 v59, v59, v202
	v_sub_f32_e32 v60, v60, v202
	v_sub_f32_e32 v61, v61, v202
	v_sub_f32_e32 v62, v62, v202
	v_sub_f32_e32 v63, v63, v202
	v_sub_f32_e32 v176, 0, v195
	v_sub_f32_e32 v177, 0, v195
	v_sub_f32_e32 v178, 0, v195
	v_sub_f32_e32 v179, 0, v195
	v_sub_f32_e32 v180, 0, v195
	v_sub_f32_e32 v181, 0, v195
	v_sub_f32_e32 v182, 0, v195
	v_sub_f32_e32 v183, 0, v195
	v_sub_f32_e32 v184, 0, v195
	v_sub_f32_e32 v185, 0, v195
	v_sub_f32_e32 v186, 0, v195
	v_sub_f32_e32 v187, 0, v195
	v_sub_f32_e32 v188, 0, v195
	v_sub_f32_e32 v189, 0, v195
	v_sub_f32_e32 v190, 0, v195
	v_sub_f32_e32 v191, 0, v195
	v_mov_b32_e32 v220, 0x41000000
	v_mov_b32_e32 v167, 0x43800000
; #define MFMA(a, b, c) __builtin_amdgcn_mfma_f32_32x32x16_bf16((a), (b), (c), 0, 0, 0)
; DI float fexp2(float x) { return __builtin_amdgcn_exp2f(x); }
; DI void phase_attn(const Params& p, int hf, bool skipctx, char* smem, int& rot) {
;     ...
;       float ps = 0.f;
; #pragma unroll
;       for (int kb = 0; kb < 2; ++kb)
; #pragma unroll
;         for (int i = 0; i < 16; ++i) { const float e = fexp2(st[kb][i] - m_run); st[kb][i] = e; ps += e; }
;       l_run += ps;
; #pragma unroll
;       for (int kb = 0; kb < 2; ++kb)
; #pragma unroll
;         for (int s2 = 0; s2 < 2; ++s2) {
;           const bf16x8 pb = pack8(st[kb][8 * s2 + 0], st[kb][8 * s2 + 1], st[kb][8 * s2 + 2], st[kb][8 * s2 + 3], st[kb][8 * s2 + 4], st[kb][8 * s2 + 5], st[kb][8 * s2 + 6], st[kb][8 * s2 + 7]);
; #pragma unroll
;           for (int dvb = 0; dvb < 2; ++dvb) o[dvb] = MFMA(vf[kb][s2][dvb], pb, o[dvb]);
;         }
.Lsc0_c0_LBB0_799:
	v_exp_f32_e32 v48, v48
	v_exp_f32_e32 v49, v49
	v_exp_f32_e32 v50, v50
	v_exp_f32_e32 v51, v51
	v_exp_f32_e32 v52, v52
	v_add_f32_e32 v195, v49, v48
	v_exp_f32_e32 v53, v53
	v_add_f32_e32 v195, v50, v195
	v_exp_f32_e32 v54, v54
	v_add_f32_e32 v195, v51, v195
	v_exp_f32_e32 v55, v55
	v_add_f32_e32 v195, v52, v195
	v_exp_f32_e32 v56, v56
	v_add_f32_e32 v195, v53, v195
	v_exp_f32_e32 v57, v57
	v_add_f32_e32 v195, v54, v195
	v_exp_f32_e32 v58, v58
	v_add_f32_e32 v195, v55, v195
	v_exp_f32_e32 v59, v59
	v_add_f32_e32 v195, v56, v195
	v_exp_f32_e32 v60, v60
	v_add_f32_e32 v195, v57, v195
	v_exp_f32_e32 v61, v61
	v_add_f32_e32 v195, v58, v195
	v_exp_f32_e32 v62, v62
	v_add_f32_e32 v195, v59, v195
	v_exp_f32_e32 v63, v63
	v_add_f32_e32 v195, v60, v195
	v_exp_f32_e32 v200, v32
	v_add_f32_e32 v195, v61, v195
	v_exp_f32_e32 v201, v33
	v_add_f32_e32 v32, v62, v195
	v_exp_f32_e32 v195, v34
	v_add_f32_e32 v32, v63, v32
	v_exp_f32_e32 v202, v35
	v_add_f32_e32 v32, v200, v32
	v_exp_f32_e32 v36, v36
	v_add_f32_e32 v32, v201, v32
	v_exp_f32_e32 v37, v37
	v_add_f32_e32 v32, v195, v32
	v_add_f32_e32 v32, v202, v32
	v_add_f32_e32 v32, v36, v32
	v_add_f32_e32 v203, v37, v32
	v_cvt_pk_bf16_f32 v32, v48, v49
	v_cvt_pk_bf16_f32 v33, v50, v51
	v_cvt_pk_bf16_f32 v34, v52, v53
	v_cvt_pk_bf16_f32 v35, v54, v55
	v_exp_f32_e32 v38, v38
	s_waitcnt lgkmcnt(7)
	v_mfma_f32_32x32x16_bf16 v[16:31], v[156:159], v[32:35], v[16:31]
	v_exp_f32_e32 v39, v39
	v_exp_f32_e32 v40, v40
	v_add_f32_e32 v48, v38, v203
	v_exp_f32_e32 v42, v42
	s_waitcnt lgkmcnt(5)
	v_mfma_f32_32x32x16_bf16 v[0:15], v[152:155], v[32:35], v[0:15]
	v_exp_f32_e32 v41, v41
	v_cvt_pk_bf16_f32 v32, v56, v57
	v_cvt_pk_bf16_f32 v33, v58, v59
	v_cvt_pk_bf16_f32 v34, v60, v61
	v_cvt_pk_bf16_f32 v35, v62, v63
	v_add_f32_e32 v48, v39, v48
	s_nop 0
	v_mfma_f32_32x32x16_bf16 v[16:31], v[148:151], v[32:35], v[16:31]
	v_exp_f32_e32 v43, v43
	v_add_f32_e32 v48, v40, v48
	v_exp_f32_e32 v44, v44
	v_add_f32_e32 v48, v41, v48
	s_waitcnt lgkmcnt(4)
	v_mfma_f32_32x32x16_bf16 v[0:15], v[144:147], v[32:35], v[0:15]
	v_add_f32_e32 v32, v42, v48
	v_add_f32_e32 v32, v43, v32
	v_add_f32_e32 v48, v44, v32
	v_cvt_pk_bf16_f32 v32, v200, v201
	v_cvt_pk_bf16_f32 v33, v195, v202
	v_cvt_pk_bf16_f32 v34, v36, v37
	v_cvt_pk_bf16_f32 v35, v38, v39
	v_exp_f32_e32 v36, v45
	s_waitcnt lgkmcnt(3)
	v_mfma_f32_32x32x16_bf16 v[16:31], v[140:143], v[32:35], v[16:31]
	v_exp_f32_e32 v37, v46
	v_exp_f32_e32 v38, v47
	v_add_f32_e32 v39, v36, v48
	s_waitcnt lgkmcnt(2)
	v_mfma_f32_32x32x16_bf16 v[0:15], v[136:139], v[32:35], v[0:15]
	v_add_f32_e32 v32, v37, v39
	v_add_f32_e32 v32, v38, v32
	v_add_f32_e32 v213, v213, v32
	v_cvt_pk_bf16_f32 v32, v40, v41
	v_cvt_pk_bf16_f32 v33, v42, v43
	v_cvt_pk_bf16_f32 v34, v44, v36
	v_cvt_pk_bf16_f32 v35, v37, v38
	s_waitcnt lgkmcnt(1)
	s_nop 0
	v_mfma_f32_32x32x16_bf16 v[16:31], v[132:135], v[32:35], v[16:31]
	ds_read_b128 v[36:39], v210 offset:13312
	ds_read_b128 v[132:135], v210 offset:13344
	ds_read_b128 v[136:139], v210 offset:13376
	ds_read_b128 v[140:143], v210 offset:13408
	ds_read_b128 v[144:147], v210 offset:13440
	ds_read_b128 v[148:151], v210 offset:13472
	ds_read_b128 v[40:43], v210 offset:19968
	ds_read_b128 v[152:155], v210 offset:20000
	ds_read_b128 v[156:159], v210 offset:20032
	ds_read_b128 v[234:237], v210 offset:20064
	ds_read_b128 v[238:241], v210 offset:20096
	ds_read_b128 v[242:245], v210 offset:20128
	s_waitcnt lgkmcnt(12)
	v_mfma_f32_32x32x16_bf16 v[0:15], v[128:131], v[32:35], v[0:15]
	s_branch .Lsc0_mj0
; #define MFMA(a, b, c) __builtin_amdgcn_mfma_f32_32x32x16_bf16((a), (b), (c), 0, 0, 0)
; DI float fexp2(float x) { return __builtin_amdgcn_exp2f(x); }
; DI f32x16 zero16() { f32x16 z; for (int i = 0; i < 16; ++i) z[i] = 0.f; return z; }
; DI void phase_attn(const Params& p, int hf, bool skipctx, char* smem, int& rot) {
;     ...
;       const char* sk = smem + buf * STG + half * 64 * KROW; const char* sv = smem + buf * STG + KB_ + half * 128;
;       f32x16 st[2]; st[0] = zero16(); st[1] = zero16();
;       {
;         bf16x8 kf[2][6];
; #pragma unroll
;         for (int kb = 0; kb < 2; ++kb)
; #pragma unroll
;           for (int ks = 0; ks < 6; ++ks) kf[kb][ks] = *(const bf16x8*)(sk + (kb * 32 + r) * KROW + (ks * 16 + h * 8) * 2);
;         __builtin_amdgcn_sched_barrier(0);
; #pragma unroll
;         for (int ks = 0; ks < 6; ++ks)
; #pragma unroll
;           for (int kb = 0; kb < 2; ++kb) st[kb] = MFMA(kf[kb][ks], qf[ks], st[kb]);
;         __builtin_amdgcn_sched_barrier(0);
;       }
;       bf16x8 vf[2][2][2];
; #pragma unroll
;       for (int kb = 0; kb < 2; ++kb)
; #pragma unroll
;         for (int s2 = 0; s2 < 2; ++s2)
; #pragma unroll
;           for (int dvb = 0; dvb < 2; ++dvb) {
;             const char* vp = sv + (dvb * 32 + r) * VROW + (kb * 32 + 16 * s2 + 4 * h) * 2;
;             const s16x4 lo = *(const s16x4*)vp, hi = *(const s16x4*)(vp + 16);
;             vf[kb][s2][dvb] = __builtin_shufflevector(lo, hi, 0, 1, 2, 3, 4, 5, 6, 7);
;           }
;       float mx = st[0][0];
; #pragma unroll
;       for (int i = 0; i < 16; ++i) { mx = fmaxf(mx, st[0][i]); mx = fmaxf(mx, st[1][i]); }
;       if (__any(mx > m_run + 8.f)) {
;         mx = fmaxf(mx, __shfl_xor(mx, 32));
;         const float m_new = fmaxf(m_run, mx);
;         const float alpha = fexp2(m_run - m_new);
;         m_run = m_new;
;         l_run *= alpha;
; #pragma unroll
;         for (int i = 0; i < 16; ++i) { o[0][i] *= alpha; o[1][i] *= alpha; }
;       }
.Lsc0_fb1:
	ds_read_b128 v[36:39], v210 offset:13312
	ds_read_b128 v[132:135], v210 offset:13344
	ds_read_b128 v[136:139], v210 offset:13376
	ds_read_b128 v[140:143], v210 offset:13408
	ds_read_b128 v[144:147], v210 offset:13440
	ds_read_b128 v[148:151], v210 offset:13472
	ds_read_b128 v[40:43], v210 offset:19968
	ds_read_b128 v[152:155], v210 offset:20000
	ds_read_b128 v[156:159], v210 offset:20032
	ds_read_b128 v[234:237], v210 offset:20064
	ds_read_b128 v[238:241], v210 offset:20096
	ds_read_b128 v[242:245], v210 offset:20128
	s_waitcnt lgkmcnt(0)
	s_waitcnt lgkmcnt(11)
	v_mfma_f32_32x32x16_bf16 v[48:63], v[36:39], v[64:67], v[176:191]
	s_waitcnt lgkmcnt(5)
	v_mfma_f32_32x32x16_bf16 v[32:47], v[40:43], v[64:67], v[176:191]
	v_mfma_f32_32x32x16_bf16 v[48:63], v[132:135], v[68:71], v[48:63]
	s_waitcnt lgkmcnt(4)
	v_mfma_f32_32x32x16_bf16 v[32:47], v[152:155], v[68:71], v[32:47]
	v_mfma_f32_32x32x16_bf16 v[48:63], v[136:139], v[72:75], v[48:63]
	s_waitcnt lgkmcnt(3)
	v_mfma_f32_32x32x16_bf16 v[32:47], v[156:159], v[72:75], v[32:47]
	v_mfma_f32_32x32x16_bf16 v[48:63], v[140:143], v[88:91], v[48:63]
	s_waitcnt lgkmcnt(2)
	v_mfma_f32_32x32x16_bf16 v[32:47], v[234:237], v[88:91], v[32:47]
	v_mfma_f32_32x32x16_bf16 v[48:63], v[144:147], v[96:99], v[48:63]
	s_waitcnt lgkmcnt(1)
	v_mfma_f32_32x32x16_bf16 v[32:47], v[238:241], v[96:99], v[32:47]
	v_mfma_f32_32x32x16_bf16 v[48:63], v[148:151], v[100:103], v[48:63]
	s_waitcnt lgkmcnt(0)
	v_mfma_f32_32x32x16_bf16 v[32:47], v[242:245], v[100:103], v[32:47]
	s_nop 3
	ds_read_b128 v[156:159], v211 offset:128
	ds_read_b128 v[148:151], v211 offset:160
	ds_read_b128 v[152:155], v211 offset:8832
	ds_read_b128 v[144:147], v211 offset:8864
	ds_read_b128 v[140:143], v211 offset:192
	ds_read_b128 v[136:139], v211 offset:8896
	ds_read_b128 v[128:131], v211 offset:224
	ds_read_b128 v[132:135], v211 offset:8928
	v_max3_f32 v195, v32, v48, v49
	v_max_f32_e32 v195, v195, v33
	v_max3_f32 v195, v195, v50, v34
	v_max3_f32 v195, v195, v51, v35
	v_max3_f32 v195, v195, v52, v36
	v_max3_f32 v195, v195, v53, v37
	v_max3_f32 v195, v195, v54, v38
	v_max3_f32 v195, v195, v55, v39
	v_max3_f32 v195, v195, v56, v40
	v_max3_f32 v195, v195, v57, v41
	v_max3_f32 v195, v195, v58, v42
	v_max3_f32 v195, v195, v59, v43
	v_max3_f32 v195, v195, v60, v44
	v_max3_f32 v195, v195, v61, v45
	v_max3_f32 v195, v195, v62, v46
	v_max3_f32 v214, v195, v63, v47
	v_cmp_gt_f32_e32 vcc, v214, v220
	s_cbranch_vccz .Lsc0_c1_LBB0_801
	v_sub_f32_e32 v214, v214, v176
	v_cmp_lt_i32_e32 vcc, v224, v207
	s_nop 1
	v_cndmask_b32_e32 v195, v205, v224, vcc
	v_lshlrev_b32_e32 v195, 2, v195
	ds_bpermute_b32 v195, v195, v214
	s_waitcnt lgkmcnt(0)
	v_max3_f32 v195, v212, v214, v195
	v_sub_f32_e32 v200, v212, v195
	v_exp_f32_e32 v200, v200
	v_mov_b32_e32 v212, v195
	v_mul_f32_e32 v213, v213, v200
	v_pk_mul_f32 v[30:31], v[30:31], v[200:201] op_sel_hi:[1,0]
	v_pk_mul_f32 v[28:29], v[28:29], v[200:201] op_sel_hi:[1,0]
	v_pk_mul_f32 v[26:27], v[26:27], v[200:201] op_sel_hi:[1,0]
	v_pk_mul_f32 v[24:25], v[24:25], v[200:201] op_sel_hi:[1,0]
	v_pk_mul_f32 v[22:23], v[22:23], v[200:201] op_sel_hi:[1,0]
	v_pk_mul_f32 v[20:21], v[20:21], v[200:201] op_sel_hi:[1,0]
	v_pk_mul_f32 v[18:19], v[18:19], v[200:201] op_sel_hi:[1,0]
	v_pk_mul_f32 v[16:17], v[16:17], v[200:201] op_sel_hi:[1,0]
	v_pk_mul_f32 v[14:15], v[14:15], v[200:201] op_sel_hi:[1,0]
	v_pk_mul_f32 v[12:13], v[12:13], v[200:201] op_sel_hi:[1,0]
	v_pk_mul_f32 v[10:11], v[10:11], v[200:201] op_sel_hi:[1,0]
	v_pk_mul_f32 v[8:9], v[8:9], v[200:201] op_sel_hi:[1,0]
	v_pk_mul_f32 v[6:7], v[6:7], v[200:201] op_sel_hi:[1,0]
	v_pk_mul_f32 v[4:5], v[4:5], v[200:201] op_sel_hi:[1,0]
	v_pk_mul_f32 v[2:3], v[2:3], v[200:201] op_sel_hi:[1,0]
	v_pk_mul_f32 v[0:1], v[0:1], v[200:201] op_sel_hi:[1,0]
	v_add_f32_e32 v202, v195, v176
	v_sub_f32_e32 v32, v32, v202
	v_sub_f32_e32 v33, v33, v202
	v_sub_f32_e32 v34, v34, v202
	v_sub_f32_e32 v35, v35, v202
	v_sub_f32_e32 v36, v36, v202
	v_sub_f32_e32 v37, v37, v202
	v_sub_f32_e32 v38, v38, v202
	v_sub_f32_e32 v39, v39, v202
	v_sub_f32_e32 v40, v40, v202
	v_sub_f32_e32 v41, v41, v202
	v_sub_f32_e32 v42, v42, v202
	v_sub_f32_e32 v43, v43, v202
	v_sub_f32_e32 v44, v44, v202
	v_sub_f32_e32 v45, v45, v202
	v_sub_f32_e32 v46, v46, v202
	v_sub_f32_e32 v47, v47, v202
	v_sub_f32_e32 v48, v48, v202
	v_sub_f32_e32 v49, v49, v202
	v_sub_f32_e32 v50, v50, v202
	v_sub_f32_e32 v51, v51, v202
	v_sub_f32_e32 v52, v52, v202
	v_sub_f32_e32 v53, v53, v202
	v_sub_f32_e32 v54, v54, v202
	v_sub_f32_e32 v55, v55, v202
	v_sub_f32_e32 v56, v56, v202
	v_sub_f32_e32 v57, v57, v202
	v_sub_f32_e32 v58, v58, v202
	v_sub_f32_e32 v59, v59, v202
	v_sub_f32_e32 v60, v60, v202
	v_sub_f32_e32 v61, v61, v202
	v_sub_f32_e32 v62, v62, v202
	v_sub_f32_e32 v63, v63, v202
	v_sub_f32_e32 v176, 0, v195
	v_sub_f32_e32 v177, 0, v195
	v_sub_f32_e32 v178, 0, v195
	v_sub_f32_e32 v179, 0, v195
	v_sub_f32_e32 v180, 0, v195
	v_sub_f32_e32 v181, 0, v195
	v_sub_f32_e32 v182, 0, v195
	v_sub_f32_e32 v183, 0, v195
	v_sub_f32_e32 v184, 0, v195
	v_sub_f32_e32 v185, 0, v195
	v_sub_f32_e32 v186, 0, v195
	v_sub_f32_e32 v187, 0, v195
	v_sub_f32_e32 v188, 0, v195
	v_sub_f32_e32 v189, 0, v195
	v_sub_f32_e32 v190, 0, v195
	v_sub_f32_e32 v191, 0, v195
	v_mov_b32_e32 v220, 0x41000000
	v_mov_b32_e32 v167, 0x43800000

; #define MFMA(a, b, c) __builtin_amdgcn_mfma_f32_32x32x16_bf16((a), (b), (c), 0, 0, 0)
; DI float fexp2(float x) { return __builtin_amdgcn_exp2f(x); }
; DI f32x16 zero16() { f32x16 z; for (int i = 0; i < 16; ++i) z[i] = 0.f; return z; }
; DI void phase_attn(const Params& p, int hf, bool skipctx, char* smem, int& rot) {
;     ...
;       const char* sk = smem + buf * STG + half * 64 * KROW; const char* sv = smem + buf * STG + KB_ + half * 128;
;       f32x16 st[2]; st[0] = zero16(); st[1] = zero16();
;       {
;         bf16x8 kf[2][6];
; #pragma unroll
;         for (int kb = 0; kb < 2; ++kb)
; #pragma unroll
;           for (int ks = 0; ks < 6; ++ks) kf[kb][ks] = *(const bf16x8*)(sk + (kb * 32 + r) * KROW + (ks * 16 + h * 8) * 2);
;         __builtin_amdgcn_sched_barrier(0);
; #pragma unroll
;         for (int ks = 0; ks < 6; ++ks)
; #pragma unroll
;           for (int kb = 0; kb < 2; ++kb) st[kb] = MFMA(kf[kb][ks], qf[ks], st[kb]);
;         __builtin_amdgcn_sched_barrier(0);
;       }
;       bf16x8 vf[2][2][2];
; #pragma unroll
;       for (int kb = 0; kb < 2; ++kb)
; #pragma unroll
;         for (int s2 = 0; s2 < 2; ++s2)
; #pragma unroll
;           for (int dvb = 0; dvb < 2; ++dvb) {
;             const char* vp = sv + (dvb * 32 + r) * VROW + (kb * 32 + 16 * s2 + 4 * h) * 2;
;             const s16x4 lo = *(const s16x4*)vp, hi = *(const s16x4*)(vp + 16);
;             vf[kb][s2][dvb] = __builtin_shufflevector(lo, hi, 0, 1, 2, 3, 4, 5, 6, 7);
;           }
;       float mx = st[0][0];
; #pragma unroll
;       for (int i = 0; i < 16; ++i) { mx = fmaxf(mx, st[0][i]); mx = fmaxf(mx, st[1][i]); }
;       if (__any(mx > m_run + 8.f)) {
;         mx = fmaxf(mx, __shfl_xor(mx, 32));
;         const float m_new = fmaxf(m_run, mx);
;         const float alpha = fexp2(m_run - m_new);
;         m_run = m_new;
;         l_run *= alpha;
; #pragma unroll
;         for (int i = 0; i < 16; ++i) { o[0][i] *= alpha; o[1][i] *= alpha; }
;       }
;       float ps = 0.f;
; #pragma unroll
;       for (int kb = 0; kb < 2; ++kb)
; #pragma unroll
;         for (int i = 0; i < 16; ++i) { const float e = fexp2(st[kb][i] - m_run); st[kb][i] = e; ps += e; }
;       l_run += ps;
.Lsc0_c1_LBB0_803:
	v_add_f32_e32 v48, v49, v48
	v_add_f32_e32 v48, v50, v48
	v_add_f32_e32 v48, v51, v48
	v_add_f32_e32 v48, v52, v48
	v_add_f32_e32 v48, v53, v48
	v_add_f32_e32 v48, v54, v48
	v_add_f32_e32 v48, v55, v48
	v_add_f32_e32 v48, v56, v48
	v_add_f32_e32 v48, v57, v48
	v_add_f32_e32 v48, v58, v48
	v_add_f32_e32 v48, v59, v48
	v_add_f32_e32 v48, v60, v48
	v_add_f32_e32 v48, v61, v48
	v_add_f32_e32 v48, v62, v48
	v_add_f32_e32 v48, v63, v48
	v_add_f32_e32 v32, v32, v48
	v_add_f32_e32 v32, v33, v32
	v_add_f32_e32 v32, v34, v32
	v_add_f32_e32 v32, v35, v32
	v_add_f32_e32 v32, v36, v32
	v_add_f32_e32 v32, v37, v32
	v_add_f32_e32 v32, v38, v32
	v_add_f32_e32 v32, v39, v32
	v_add_f32_e32 v32, v40, v32
	v_add_f32_e32 v32, v41, v32
	v_add_f32_e32 v32, v42, v32
	v_add_f32_e32 v32, v43, v32
	v_add_f32_e32 v32, v44, v32
	v_add_f32_e32 v32, v45, v32
	v_add_f32_e32 v32, v46, v32
	v_add_f32_e32 v32, v47, v32
	v_add_f32_e32 v213, v213, v32
	ds_read_b128 v[32:35], v210 offset:44032
	ds_read_b128 v[128:131], v210 offset:44064
	ds_read_b128 v[132:135], v210 offset:44096
	ds_read_b128 v[136:139], v210 offset:44128
	ds_read_b128 v[140:143], v210 offset:44160
	ds_read_b128 v[144:147], v210 offset:44192
	ds_read_b128 v[36:39], v210 offset:50688
	ds_read_b128 v[148:151], v210 offset:50720
	ds_read_b128 v[152:155], v210 offset:50752
	ds_read_b128 v[156:159], v210 offset:50784
	ds_read_b128 v[214:217], v210 offset:50816
	ds_read_b128 v[234:237], v210 offset:50848
	s_branch .Lsc0_mj1
.Lsc0_fb2:
	ds_read_b128 v[32:35], v210 offset:44032
	ds_read_b128 v[128:131], v210 offset:44064
	ds_read_b128 v[132:135], v210 offset:44096
	ds_read_b128 v[136:139], v210 offset:44128
	ds_read_b128 v[140:143], v210 offset:44160
	ds_read_b128 v[144:147], v210 offset:44192
	ds_read_b128 v[36:39], v210 offset:50688
	ds_read_b128 v[148:151], v210 offset:50720
	ds_read_b128 v[152:155], v210 offset:50752
	ds_read_b128 v[156:159], v210 offset:50784
	ds_read_b128 v[214:217], v210 offset:50816
	ds_read_b128 v[234:237], v210 offset:50848
	s_waitcnt lgkmcnt(0)
	s_waitcnt lgkmcnt(11)
	v_mfma_f32_32x32x16_bf16 v[48:63], v[32:35], v[64:67], v[176:191]
	s_waitcnt lgkmcnt(5)
	v_mfma_f32_32x32x16_bf16 v[32:47], v[36:39], v[64:67], v[176:191]
	v_mfma_f32_32x32x16_bf16 v[48:63], v[128:131], v[68:71], v[48:63]
	s_waitcnt lgkmcnt(4)
	v_mfma_f32_32x32x16_bf16 v[32:47], v[148:151], v[68:71], v[32:47]
	v_mfma_f32_32x32x16_bf16 v[48:63], v[132:135], v[72:75], v[48:63]
	s_waitcnt lgkmcnt(3)
	v_mfma_f32_32x32x16_bf16 v[32:47], v[152:155], v[72:75], v[32:47]
	v_mfma_f32_32x32x16_bf16 v[48:63], v[136:139], v[88:91], v[48:63]
	s_waitcnt lgkmcnt(2)
	v_mfma_f32_32x32x16_bf16 v[32:47], v[156:159], v[88:91], v[32:47]
	v_mfma_f32_32x32x16_bf16 v[48:63], v[140:143], v[96:99], v[48:63]
	s_waitcnt lgkmcnt(1)
	v_mfma_f32_32x32x16_bf16 v[32:47], v[214:217], v[96:99], v[32:47]
	v_mfma_f32_32x32x16_bf16 v[48:63], v[144:147], v[100:103], v[48:63]
	s_waitcnt lgkmcnt(0)
	v_mfma_f32_32x32x16_bf16 v[32:47], v[234:237], v[100:103], v[32:47]
	s_nop 3
	ds_read_b128 v[152:155], v211 offset:52736
	ds_read_b128 v[156:159], v211 offset:44032
	ds_read_b128 v[148:151], v211 offset:44064
	ds_read_b128 v[144:147], v211 offset:52768
	ds_read_b128 v[140:143], v211 offset:44096
	ds_read_b128 v[136:139], v211 offset:52800
	ds_read_b128 v[132:135], v211 offset:44128
	ds_read_b128 v[128:131], v211 offset:52832
	v_max3_f32 v195, v32, v48, v49
	v_max_f32_e32 v195, v195, v33
	v_max3_f32 v195, v195, v50, v34
	v_max3_f32 v195, v195, v51, v35
	v_max3_f32 v195, v195, v52, v36
	v_max3_f32 v195, v195, v53, v37
	v_max3_f32 v195, v195, v54, v38
	v_max3_f32 v195, v195, v55, v39
	v_max3_f32 v195, v195, v56, v40
	v_max3_f32 v195, v195, v57, v41
	v_max3_f32 v195, v195, v58, v42
	v_max3_f32 v195, v195, v59, v43
	v_max3_f32 v195, v195, v60, v44
	v_max3_f32 v195, v195, v61, v45
	v_max3_f32 v195, v195, v62, v46
	v_max3_f32 v215, v195, v63, v47
	v_cmp_gt_f32_e32 vcc, v215, v220
	s_cbranch_vccz .Lsc0_c2_LBB0_805
	v_sub_f32_e32 v215, v215, v176
	v_cmp_lt_i32_e32 vcc, v224, v207
	s_nop 1
	v_cndmask_b32_e32 v195, v205, v224, vcc
	v_lshlrev_b32_e32 v195, 2, v195
	ds_bpermute_b32 v195, v195, v215
	s_waitcnt lgkmcnt(0)
	v_max3_f32 v195, v212, v215, v195
	v_sub_f32_e32 v200, v212, v195
	v_exp_f32_e32 v200, v200
	v_mov_b32_e32 v212, v195
	v_mul_f32_e32 v213, v213, v200
	v_pk_mul_f32 v[30:31], v[30:31], v[200:201] op_sel_hi:[1,0]
	v_pk_mul_f32 v[28:29], v[28:29], v[200:201] op_sel_hi:[1,0]
	v_pk_mul_f32 v[26:27], v[26:27], v[200:201] op_sel_hi:[1,0]
	v_pk_mul_f32 v[24:25], v[24:25], v[200:201] op_sel_hi:[1,0]
	v_pk_mul_f32 v[22:23], v[22:23], v[200:201] op_sel_hi:[1,0]
	v_pk_mul_f32 v[20:21], v[20:21], v[200:201] op_sel_hi:[1,0]
	v_pk_mul_f32 v[18:19], v[18:19], v[200:201] op_sel_hi:[1,0]
	v_pk_mul_f32 v[16:17], v[16:17], v[200:201] op_sel_hi:[1,0]
	v_pk_mul_f32 v[14:15], v[14:15], v[200:201] op_sel_hi:[1,0]
	v_pk_mul_f32 v[12:13], v[12:13], v[200:201] op_sel_hi:[1,0]
	v_pk_mul_f32 v[10:11], v[10:11], v[200:201] op_sel_hi:[1,0]
	v_pk_mul_f32 v[8:9], v[8:9], v[200:201] op_sel_hi:[1,0]
	v_pk_mul_f32 v[6:7], v[6:7], v[200:201] op_sel_hi:[1,0]
	v_pk_mul_f32 v[4:5], v[4:5], v[200:201] op_sel_hi:[1,0]
	v_pk_mul_f32 v[2:3], v[2:3], v[200:201] op_sel_hi:[1,0]
	v_pk_mul_f32 v[0:1], v[0:1], v[200:201] op_sel_hi:[1,0]
	v_add_f32_e32 v202, v195, v176
	v_sub_f32_e32 v32, v32, v202
	v_sub_f32_e32 v33, v33, v202
	v_sub_f32_e32 v34, v34, v202
	v_sub_f32_e32 v35, v35, v202
	v_sub_f32_e32 v36, v36, v202
	v_sub_f32_e32 v37, v37, v202
	v_sub_f32_e32 v38, v38, v202
	v_sub_f32_e32 v39, v39, v202
	v_sub_f32_e32 v40, v40, v202
	v_sub_f32_e32 v41, v41, v202
	v_sub_f32_e32 v42, v42, v202
	v_sub_f32_e32 v43, v43, v202
	v_sub_f32_e32 v44, v44, v202
	v_sub_f32_e32 v45, v45, v202
	v_sub_f32_e32 v46, v46, v202
	v_sub_f32_e32 v47, v47, v202
	v_sub_f32_e32 v48, v48, v202
	v_sub_f32_e32 v49, v49, v202
	v_sub_f32_e32 v50, v50, v202
	v_sub_f32_e32 v51, v51, v202
	v_sub_f32_e32 v52, v52, v202
	v_sub_f32_e32 v53, v53, v202
	v_sub_f32_e32 v54, v54, v202
	v_sub_f32_e32 v55, v55, v202
	v_sub_f32_e32 v56, v56, v202
	v_sub_f32_e32 v57, v57, v202
	v_sub_f32_e32 v58, v58, v202
	v_sub_f32_e32 v59, v59, v202
	v_sub_f32_e32 v60, v60, v202
	v_sub_f32_e32 v61, v61, v202
	v_sub_f32_e32 v62, v62, v202
	v_sub_f32_e32 v63, v63, v202
	v_sub_f32_e32 v176, 0, v195
	v_sub_f32_e32 v177, 0, v195
	v_sub_f32_e32 v178, 0, v195
	v_sub_f32_e32 v179, 0, v195
	v_sub_f32_e32 v180, 0, v195
	v_sub_f32_e32 v181, 0, v195
	v_sub_f32_e32 v182, 0, v195
	v_sub_f32_e32 v183, 0, v195
	v_sub_f32_e32 v184, 0, v195
	v_sub_f32_e32 v185, 0, v195
	v_sub_f32_e32 v186, 0, v195
	v_sub_f32_e32 v187, 0, v195
	v_sub_f32_e32 v188, 0, v195
	v_sub_f32_e32 v189, 0, v195
	v_sub_f32_e32 v190, 0, v195
	v_sub_f32_e32 v191, 0, v195
	v_mov_b32_e32 v220, 0x41000000
	v_mov_b32_e32 v167, 0x43800000
; #define MFMA(a, b, c) __builtin_amdgcn_mfma_f32_32x32x16_bf16((a), (b), (c), 0, 0, 0)
; DI float fexp2(float x) { return __builtin_amdgcn_exp2f(x); }
; DI void phase_attn(const Params& p, int hf, bool skipctx, char* smem, int& rot) {
;     ...
;       float ps = 0.f;
; #pragma unroll
;       for (int kb = 0; kb < 2; ++kb)
; #pragma unroll
;         for (int i = 0; i < 16; ++i) { const float e = fexp2(st[kb][i] - m_run); st[kb][i] = e; ps += e; }
;       l_run += ps;
; #pragma unroll
;       for (int kb = 0; kb < 2; ++kb)
; #pragma unroll
;         for (int s2 = 0; s2 < 2; ++s2) {
;           const bf16x8 pb = pack8(st[kb][8 * s2 + 0], st[kb][8 * s2 + 1], st[kb][8 * s2 + 2], st[kb][8 * s2 + 3], st[kb][8 * s2 + 4], st[kb][8 * s2 + 5], st[kb][8 * s2 + 6], st[kb][8 * s2 + 7]);
; #pragma unroll
;           for (int dvb = 0; dvb < 2; ++dvb) o[dvb] = MFMA(vf[kb][s2][dvb], pb, o[dvb]);
;         }
.Lsc0_c2_LBB0_805:
	v_exp_f32_e32 v48, v48
	v_exp_f32_e32 v49, v49
	v_exp_f32_e32 v50, v50
	v_exp_f32_e32 v51, v51
	v_exp_f32_e32 v52, v52
	v_add_f32_e32 v195, v49, v48
	v_exp_f32_e32 v53, v53
	v_add_f32_e32 v195, v50, v195
	v_exp_f32_e32 v54, v54
	v_add_f32_e32 v195, v51, v195
	v_exp_f32_e32 v55, v55
	v_add_f32_e32 v195, v52, v195
	v_exp_f32_e32 v56, v56
	v_add_f32_e32 v195, v53, v195
	v_exp_f32_e32 v57, v57
	v_add_f32_e32 v195, v54, v195
	v_exp_f32_e32 v58, v58
	v_add_f32_e32 v195, v55, v195
	v_exp_f32_e32 v59, v59
	v_add_f32_e32 v195, v56, v195
	v_exp_f32_e32 v60, v60
	v_add_f32_e32 v195, v57, v195
	v_exp_f32_e32 v61, v61
	v_add_f32_e32 v195, v58, v195
	v_exp_f32_e32 v62, v62
	v_add_f32_e32 v195, v59, v195
	v_exp_f32_e32 v63, v63
	v_add_f32_e32 v195, v60, v195
	v_exp_f32_e32 v200, v32
	v_add_f32_e32 v195, v61, v195
	v_exp_f32_e32 v201, v33
	v_add_f32_e32 v32, v62, v195
	v_exp_f32_e32 v195, v34
	v_add_f32_e32 v32, v63, v32
	v_exp_f32_e32 v202, v35
	v_add_f32_e32 v32, v200, v32
	v_exp_f32_e32 v36, v36
	v_add_f32_e32 v32, v201, v32
	v_exp_f32_e32 v37, v37
	v_add_f32_e32 v32, v195, v32
	v_add_f32_e32 v32, v202, v32
	v_add_f32_e32 v32, v36, v32
	v_add_f32_e32 v203, v37, v32
	v_cvt_pk_bf16_f32 v32, v48, v49
	v_cvt_pk_bf16_f32 v33, v50, v51
	v_cvt_pk_bf16_f32 v34, v52, v53
	v_cvt_pk_bf16_f32 v35, v54, v55
	v_exp_f32_e32 v38, v38
	s_waitcnt lgkmcnt(6)
	v_mfma_f32_32x32x16_bf16 v[16:31], v[156:159], v[32:35], v[16:31]
	v_exp_f32_e32 v39, v39
	v_exp_f32_e32 v40, v40
	v_add_f32_e32 v48, v38, v203
	v_exp_f32_e32 v42, v42
	v_mfma_f32_32x32x16_bf16 v[0:15], v[152:155], v[32:35], v[0:15]
	v_exp_f32_e32 v41, v41
	v_cvt_pk_bf16_f32 v32, v56, v57
	v_cvt_pk_bf16_f32 v33, v58, v59
	v_cvt_pk_bf16_f32 v34, v60, v61
	v_cvt_pk_bf16_f32 v35, v62, v63
	v_add_f32_e32 v48, v39, v48
	s_waitcnt lgkmcnt(5)
	v_mfma_f32_32x32x16_bf16 v[16:31], v[148:151], v[32:35], v[16:31]
	v_exp_f32_e32 v43, v43
	v_add_f32_e32 v48, v40, v48
	v_exp_f32_e32 v44, v44
	v_add_f32_e32 v48, v41, v48
	s_waitcnt lgkmcnt(4)
	v_mfma_f32_32x32x16_bf16 v[0:15], v[144:147], v[32:35], v[0:15]
	v_add_f32_e32 v32, v42, v48
	v_add_f32_e32 v32, v43, v32
	v_add_f32_e32 v48, v44, v32
	v_cvt_pk_bf16_f32 v32, v200, v201
	v_cvt_pk_bf16_f32 v33, v195, v202
	v_cvt_pk_bf16_f32 v34, v36, v37
	v_cvt_pk_bf16_f32 v35, v38, v39
	v_exp_f32_e32 v36, v45
	s_waitcnt lgkmcnt(3)
	v_mfma_f32_32x32x16_bf16 v[16:31], v[140:143], v[32:35], v[16:31]
	v_exp_f32_e32 v37, v46
	v_exp_f32_e32 v38, v47
	v_add_f32_e32 v39, v36, v48
	s_waitcnt lgkmcnt(2)
	v_mfma_f32_32x32x16_bf16 v[0:15], v[136:139], v[32:35], v[0:15]
	v_add_f32_e32 v32, v37, v39
	v_add_f32_e32 v32, v38, v32
	v_add_f32_e32 v213, v213, v32
	v_cvt_pk_bf16_f32 v32, v40, v41
	v_cvt_pk_bf16_f32 v33, v42, v43
	v_cvt_pk_bf16_f32 v34, v44, v36
	v_cvt_pk_bf16_f32 v35, v37, v38
	s_waitcnt lgkmcnt(1)
	s_nop 0
	v_mfma_f32_32x32x16_bf16 v[16:31], v[132:135], v[32:35], v[16:31]
	ds_read_b128 v[36:39], v210 offset:57344
	ds_read_b128 v[132:135], v210 offset:57376
	ds_read_b128 v[136:139], v210 offset:57408
	ds_read_b128 v[140:143], v210 offset:57440
	ds_read_b128 v[144:147], v210 offset:57472
	ds_read_b128 v[148:151], v210 offset:57504
	ds_read_b128 v[40:43], v210 offset:64000
	ds_read_b128 v[152:155], v210 offset:64032
	ds_read_b128 v[156:159], v210 offset:64064
	ds_read_b128 v[216:219], v210 offset:64096
	ds_read_b128 v[234:237], v210 offset:64128
	ds_read_b128 v[238:241], v210 offset:64160
	s_waitcnt lgkmcnt(12)
	v_mfma_f32_32x32x16_bf16 v[0:15], v[128:131], v[32:35], v[0:15]
	s_branch .Lsc0_mj2
; #define MFMA(a, b, c) __builtin_amdgcn_mfma_f32_32x32x16_bf16((a), (b), (c), 0, 0, 0)
; DI float fexp2(float x) { return __builtin_amdgcn_exp2f(x); }
; DI f32x16 zero16() { f32x16 z; for (int i = 0; i < 16; ++i) z[i] = 0.f; return z; }
; DI void phase_attn(const Params& p, int hf, bool skipctx, char* smem, int& rot) {
;     ...
;       const char* sk = smem + buf * STG + half * 64 * KROW; const char* sv = smem + buf * STG + KB_ + half * 128;
;       f32x16 st[2]; st[0] = zero16(); st[1] = zero16();
;       {
;         bf16x8 kf[2][6];
; #pragma unroll
;         for (int kb = 0; kb < 2; ++kb)
; #pragma unroll
;           for (int ks = 0; ks < 6; ++ks) kf[kb][ks] = *(const bf16x8*)(sk + (kb * 32 + r) * KROW + (ks * 16 + h * 8) * 2);
;         __builtin_amdgcn_sched_barrier(0);
; #pragma unroll
;         for (int ks = 0; ks < 6; ++ks)
; #pragma unroll
;           for (int kb = 0; kb < 2; ++kb) st[kb] = MFMA(kf[kb][ks], qf[ks], st[kb]);
;         __builtin_amdgcn_sched_barrier(0);
;       }
;       bf16x8 vf[2][2][2];
; #pragma unroll
;       for (int kb = 0; kb < 2; ++kb)
; #pragma unroll
;         for (int s2 = 0; s2 < 2; ++s2)
; #pragma unroll
;           for (int dvb = 0; dvb < 2; ++dvb) {
;             const char* vp = sv + (dvb * 32 + r) * VROW + (kb * 32 + 16 * s2 + 4 * h) * 2;
;             const s16x4 lo = *(const s16x4*)vp, hi = *(const s16x4*)(vp + 16);
;             vf[kb][s2][dvb] = __builtin_shufflevector(lo, hi, 0, 1, 2, 3, 4, 5, 6, 7);
;           }
;       float mx = st[0][0];
; #pragma unroll
;       for (int i = 0; i < 16; ++i) { mx = fmaxf(mx, st[0][i]); mx = fmaxf(mx, st[1][i]); }
;       if (__any(mx > m_run + 8.f)) {
;         mx = fmaxf(mx, __shfl_xor(mx, 32));
;         const float m_new = fmaxf(m_run, mx);
;         const float alpha = fexp2(m_run - m_new);
;         m_run = m_new;
;         l_run *= alpha;
; #pragma unroll
;         for (int i = 0; i < 16; ++i) { o[0][i] *= alpha; o[1][i] *= alpha; }
;       }
.Lsc0_fb3:
	ds_read_b128 v[36:39], v210 offset:57344
	ds_read_b128 v[132:135], v210 offset:57376
	ds_read_b128 v[136:139], v210 offset:57408
	ds_read_b128 v[140:143], v210 offset:57440
	ds_read_b128 v[144:147], v210 offset:57472
	ds_read_b128 v[148:151], v210 offset:57504
	ds_read_b128 v[40:43], v210 offset:64000
	ds_read_b128 v[152:155], v210 offset:64032
	ds_read_b128 v[156:159], v210 offset:64064
	ds_read_b128 v[216:219], v210 offset:64096
	ds_read_b128 v[234:237], v210 offset:64128
	ds_read_b128 v[238:241], v210 offset:64160
	s_waitcnt lgkmcnt(0)
	s_waitcnt lgkmcnt(11)
	v_mfma_f32_32x32x16_bf16 v[48:63], v[36:39], v[64:67], v[176:191]
	s_waitcnt lgkmcnt(5)
	v_mfma_f32_32x32x16_bf16 v[32:47], v[40:43], v[64:67], v[176:191]
	v_mfma_f32_32x32x16_bf16 v[48:63], v[132:135], v[68:71], v[48:63]
	s_waitcnt lgkmcnt(4)
	v_mfma_f32_32x32x16_bf16 v[32:47], v[152:155], v[68:71], v[32:47]
	v_mfma_f32_32x32x16_bf16 v[48:63], v[136:139], v[72:75], v[48:63]
	s_waitcnt lgkmcnt(3)
	v_mfma_f32_32x32x16_bf16 v[32:47], v[156:159], v[72:75], v[32:47]
	v_mfma_f32_32x32x16_bf16 v[48:63], v[140:143], v[88:91], v[48:63]
	s_waitcnt lgkmcnt(2)
	v_mfma_f32_32x32x16_bf16 v[32:47], v[216:219], v[88:91], v[32:47]
	v_mfma_f32_32x32x16_bf16 v[48:63], v[144:147], v[96:99], v[48:63]
	s_waitcnt lgkmcnt(1)
	v_mfma_f32_32x32x16_bf16 v[32:47], v[234:237], v[96:99], v[32:47]
	v_mfma_f32_32x32x16_bf16 v[48:63], v[148:151], v[100:103], v[48:63]
	s_waitcnt lgkmcnt(0)
	v_mfma_f32_32x32x16_bf16 v[32:47], v[238:241], v[100:103], v[32:47]
	s_nop 3
	ds_read_b128 v[152:155], v211 offset:52864
	ds_read_b128 v[156:159], v211 offset:44160
	ds_read_b128 v[148:151], v211 offset:44192
	ds_read_b128 v[144:147], v211 offset:52896
	ds_read_b128 v[140:143], v211 offset:44224
	ds_read_b128 v[136:139], v211 offset:52928
	ds_read_b128 v[132:135], v211 offset:44256
	ds_read_b128 v[128:131], v211 offset:52960
	v_max3_f32 v195, v32, v48, v49
	v_max_f32_e32 v195, v195, v33
	v_max3_f32 v195, v195, v50, v34
	v_max3_f32 v195, v195, v51, v35
	v_max3_f32 v195, v195, v52, v36
	v_max3_f32 v195, v195, v53, v37
	v_max3_f32 v195, v195, v54, v38
	v_max3_f32 v195, v195, v55, v39
	v_max3_f32 v195, v195, v56, v40
	v_max3_f32 v195, v195, v57, v41
	v_max3_f32 v195, v195, v58, v42
	v_max3_f32 v195, v195, v59, v43
	v_max3_f32 v195, v195, v60, v44
	v_max3_f32 v195, v195, v61, v45
	v_max3_f32 v195, v195, v62, v46
	v_max3_f32 v215, v195, v63, v47
	v_cmp_gt_f32_e32 vcc, v215, v220
	s_cbranch_vccz .Lsc0_c3_LBB0_807
	v_sub_f32_e32 v215, v215, v176
	v_cmp_lt_i32_e32 vcc, v224, v207
	s_nop 1
	v_cndmask_b32_e32 v195, v205, v224, vcc
	v_lshlrev_b32_e32 v195, 2, v195
	ds_bpermute_b32 v195, v195, v215
	s_waitcnt lgkmcnt(0)
	v_max3_f32 v195, v212, v215, v195
	v_sub_f32_e32 v200, v212, v195
	v_exp_f32_e32 v200, v200
	v_mov_b32_e32 v212, v195
	v_mul_f32_e32 v213, v213, v200
	v_pk_mul_f32 v[30:31], v[30:31], v[200:201] op_sel_hi:[1,0]
	v_pk_mul_f32 v[28:29], v[28:29], v[200:201] op_sel_hi:[1,0]
	v_pk_mul_f32 v[26:27], v[26:27], v[200:201] op_sel_hi:[1,0]
	v_pk_mul_f32 v[24:25], v[24:25], v[200:201] op_sel_hi:[1,0]
	v_pk_mul_f32 v[22:23], v[22:23], v[200:201] op_sel_hi:[1,0]
	v_pk_mul_f32 v[20:21], v[20:21], v[200:201] op_sel_hi:[1,0]
	v_pk_mul_f32 v[18:19], v[18:19], v[200:201] op_sel_hi:[1,0]
	v_pk_mul_f32 v[16:17], v[16:17], v[200:201] op_sel_hi:[1,0]
	v_pk_mul_f32 v[14:15], v[14:15], v[200:201] op_sel_hi:[1,0]
	v_pk_mul_f32 v[12:13], v[12:13], v[200:201] op_sel_hi:[1,0]
	v_pk_mul_f32 v[10:11], v[10:11], v[200:201] op_sel_hi:[1,0]
	v_pk_mul_f32 v[8:9], v[8:9], v[200:201] op_sel_hi:[1,0]
	v_pk_mul_f32 v[6:7], v[6:7], v[200:201] op_sel_hi:[1,0]
	v_pk_mul_f32 v[4:5], v[4:5], v[200:201] op_sel_hi:[1,0]
	v_pk_mul_f32 v[2:3], v[2:3], v[200:201] op_sel_hi:[1,0]
	v_pk_mul_f32 v[0:1], v[0:1], v[200:201] op_sel_hi:[1,0]
	v_add_f32_e32 v202, v195, v176
	v_sub_f32_e32 v32, v32, v202
	v_sub_f32_e32 v33, v33, v202
	v_sub_f32_e32 v34, v34, v202
	v_sub_f32_e32 v35, v35, v202
	v_sub_f32_e32 v36, v36, v202
	v_sub_f32_e32 v37, v37, v202
	v_sub_f32_e32 v38, v38, v202
	v_sub_f32_e32 v39, v39, v202
	v_sub_f32_e32 v40, v40, v202
	v_sub_f32_e32 v41, v41, v202
	v_sub_f32_e32 v42, v42, v202
	v_sub_f32_e32 v43, v43, v202
	v_sub_f32_e32 v44, v44, v202
	v_sub_f32_e32 v45, v45, v202
	v_sub_f32_e32 v46, v46, v202
	v_sub_f32_e32 v47, v47, v202
	v_sub_f32_e32 v48, v48, v202
	v_sub_f32_e32 v49, v49, v202
	v_sub_f32_e32 v50, v50, v202
	v_sub_f32_e32 v51, v51, v202
	v_sub_f32_e32 v52, v52, v202
	v_sub_f32_e32 v53, v53, v202
	v_sub_f32_e32 v54, v54, v202
	v_sub_f32_e32 v55, v55, v202
	v_sub_f32_e32 v56, v56, v202
	v_sub_f32_e32 v57, v57, v202
	v_sub_f32_e32 v58, v58, v202
	v_sub_f32_e32 v59, v59, v202
	v_sub_f32_e32 v60, v60, v202
	v_sub_f32_e32 v61, v61, v202
	v_sub_f32_e32 v62, v62, v202
	v_sub_f32_e32 v63, v63, v202
	v_sub_f32_e32 v176, 0, v195
	v_sub_f32_e32 v177, 0, v195
	v_sub_f32_e32 v178, 0, v195
	v_sub_f32_e32 v179, 0, v195
	v_sub_f32_e32 v180, 0, v195
	v_sub_f32_e32 v181, 0, v195
	v_sub_f32_e32 v182, 0, v195
	v_sub_f32_e32 v183, 0, v195
	v_sub_f32_e32 v184, 0, v195
	v_sub_f32_e32 v185, 0, v195
	v_sub_f32_e32 v186, 0, v195
	v_sub_f32_e32 v187, 0, v195
	v_sub_f32_e32 v188, 0, v195
	v_sub_f32_e32 v189, 0, v195
	v_sub_f32_e32 v190, 0, v195
	v_sub_f32_e32 v191, 0, v195
	v_mov_b32_e32 v220, 0x41000000
	v_mov_b32_e32 v167, 0x43800000

; DI float bflo(unsigned u) { return __uint_as_float(u << 16); }
; DI float bfhi(unsigned u) { return __uint_as_float(u & 0xffff0000u); }
; DI f32x16 zero16() { f32x16 z; for (int i = 0; i < 16; ++i) z[i] = 0.f; return z; }
; DI void phase_attn(const Params& p, int hf, bool skipctx, char* smem, int& rot) {
;     ...
;       uint4 qu[6];
; #pragma unroll
;       for (int ks = 0; ks < 6; ++ks) qu[ks] = *(const uint4*)(Qb + tq * 768 + head * 96 + ks * 16 + h * 8);
; #pragma unroll
;       for (int ks = 0; ks < 4; ++ks) {
;         const uint4 u = qu[ks];
;         qf[ks] = pack8(bflo(u.x) * QSCALE, bfhi(u.x) * QSCALE, bflo(u.y) * QSCALE, bfhi(u.y) * QSCALE, bflo(u.z) * QSCALE, bfhi(u.z) * QSCALE, bflo(u.w) * QSCALE, bfhi(u.w) * QSCALE);
;       }
;       const unsigned a1[4] = {qu[4].x, qu[4].y, qu[4].z, qu[4].w}, a2[4] = {qu[5].x, qu[5].y, qu[5].z, qu[5].w};
;       float o1[8], o2[8];
;       const int sq_ = s0 + w * 32 + r;
; #pragma unroll
;       for (int e = 0; e < 8; ++e) {
;         const float x1 = ((e & 1) ? bfhi(a1[e >> 1]) : bflo(a1[e >> 1])) * QSCALE;
;         const float x2 = ((e & 1) ? bfhi(a2[e >> 1]) : bflo(a2[e >> 1])) * QSCALE;
;         float cs = 1.f, sn = 0.f;
;         if (sq_ >= LC) { cs = axc[(sq_ - LC) * 16 + 8 * h + e]; sn = axs[(sq_ - LC) * 16 + 8 * h + e]; }
;         o1[e] = x1 * cs - x2 * sn; o2[e] = x1 * sn + x2 * cs;
;       }
;       qf[4] = pack8(o1[0], o1[1], o1[2], o1[3], o1[4], o1[5], o1[6], o1[7]);
;       qf[5] = pack8(o2[0], o2[1], o2[2], o2[3], o2[4], o2[5], o2[6], o2[7]);
;     }
;     const bf16_t* Kg = Kb + (size_t)(bl * 8 + head) * S * 96;
;     const bf16_t* Vg = VTb + (size_t)(bl * 8 + head) * 64 * S;
;     f32x16 o[2]; o[0] = zero16(); o[1] = zero16();
;     float m_run = -1e30f, l_run = 0.f;
;     uint4 ak0, ak1, ak2, av0, av1, bk0, bk1, bk2, bv0, bv1;
;     const int kr0 = tid / 12, kc0 = tid - kr0 * 12, kr1 = (tid + 512) / 12, kc1 = (tid + 512) - kr1 * 12, kr2 = (tid + 1024) / 12, kc2 = (tid + 1024) - kr2 * 12;
.LBB0_1059:
	s_or_b64 exec, exec, s[26:27]
	s_waitcnt vmcnt(0)
	v_lshlrev_b32_e32 v27, 16, v23
	v_lshlrev_b32_e32 v26, 16, v19
	v_pk_mul_f32 v[26:27], v[26:27], s[48:49] op_sel_hi:[1,0]
	v_lshlrev_b32_e32 v47, 16, v22
	v_pk_mul_f32 v[28:29], v[26:27], v[30:31] op_sel:[0,1] op_sel_hi:[1,0]
	v_pk_mul_f32 v[26:27], v[26:27], v[30:31]
	v_and_b32_e32 v30, 0xffff0000, v19
	v_lshlrev_b32_e32 v46, 16, v18
	v_and_b32_e32 v19, 0xffff0000, v22
	v_and_b32_e32 v18, 0xffff0000, v18
	v_and_b32_e32 v31, 0xffff0000, v23
	v_pk_mul_f32 v[46:47], v[46:47], s[48:49] op_sel_hi:[1,0]
	v_pk_mul_f32 v[22:23], v[18:19], s[48:49] op_sel_hi:[1,0]
	v_pk_mul_f32 v[48:49], v[46:47], v[42:43] op_sel:[0,1] op_sel_hi:[1,0]
	v_pk_mul_f32 v[42:43], v[46:47], v[42:43]
	v_pk_mul_f32 v[18:19], v[22:23], v[40:41] op_sel:[0,1] op_sel_hi:[1,0]
	v_pk_mul_f32 v[22:23], v[22:23], v[40:41]
	v_mov_b32_e32 v40, v42
	v_mov_b32_e32 v41, v22
	v_mov_b32_e32 v22, v43
	v_pk_add_f32 v[22:23], v[40:41], v[22:23]
	v_lshlrev_b32_e32 v41, 16, v21
	v_lshlrev_b32_e32 v40, 16, v17
	v_pk_mul_f32 v[40:41], v[40:41], s[48:49] op_sel_hi:[1,0]
	v_mov_b32_e32 v46, v48
	v_mov_b32_e32 v47, v18
	v_mov_b32_e32 v18, v49
	v_pk_mul_f32 v[42:43], v[40:41], v[32:33] op_sel:[0,1] op_sel_hi:[1,0]
	v_pk_mul_f32 v[40:41], v[40:41], v[32:33]
	v_and_b32_e32 v33, 0xffff0000, v21
	v_and_b32_e32 v32, 0xffff0000, v17
	v_pk_add_f32 v[18:19], v[46:47], v[18:19] neg_lo:[0,1] neg_hi:[0,1]
	v_pk_mul_f32 v[46:47], v[32:33], s[48:49] op_sel_hi:[1,0]
	v_mov_b32_e32 v48, v42
	v_pk_mul_f32 v[32:33], v[46:47], v[34:35] op_sel:[0,1] op_sel_hi:[1,0]
	v_pk_mul_f32 v[34:35], v[46:47], v[34:35]
	v_mov_b32_e32 v49, v32
	v_mov_b32_e32 v32, v43
	v_mov_b32_e32 v42, v40
	v_mov_b32_e32 v43, v34
	v_mov_b32_e32 v34, v41
	v_lshlrev_b32_e32 v41, 16, v20
	v_lshlrev_b32_e32 v40, 16, v16
	v_and_b32_e32 v17, 0xffff0000, v20
	v_and_b32_e32 v16, 0xffff0000, v16
	v_pk_mul_f32 v[40:41], v[40:41], s[48:49] op_sel_hi:[1,0]
	v_pk_mul_f32 v[20:21], v[16:17], s[48:49] op_sel_hi:[1,0]
	v_pk_add_f32 v[34:35], v[42:43], v[34:35]
	v_pk_mul_f32 v[42:43], v[40:41], v[38:39] op_sel:[0,1] op_sel_hi:[1,0]
	v_pk_mul_f32 v[38:39], v[40:41], v[38:39]
	v_pk_mul_f32 v[16:17], v[20:21], v[36:37] op_sel:[0,1] op_sel_hi:[1,0]
	v_pk_mul_f32 v[20:21], v[20:21], v[36:37]
	v_mov_b32_e32 v36, v38
	v_mov_b32_e32 v37, v20
	v_mov_b32_e32 v20, v39
	v_pk_add_f32 v[20:21], v[36:37], v[20:21]
	v_lshlrev_b32_e32 v36, 16, v12
	v_and_b32_e32 v37, 0xffff0000, v12
	v_lshlrev_b32_e32 v12, 16, v13
	v_and_b32_e32 v13, 0xffff0000, v13
	v_pk_mul_f32 v[12:13], v[12:13], s[48:49] op_sel_hi:[1,0]
	v_lshlrev_b32_e32 v38, 16, v14
	v_cvt_pk_bf16_f32 v65, v12, v13
	v_lshlrev_b32_e32 v12, 16, v8
	v_and_b32_e32 v13, 0xffff0000, v8
	v_lshlrev_b32_e32 v8, 16, v9
	v_and_b32_e32 v9, 0xffff0000, v9
	v_pk_mul_f32 v[8:9], v[8:9], s[48:49] op_sel_hi:[1,0]
	v_and_b32_e32 v39, 0xffff0000, v14
	v_cvt_pk_bf16_f32 v69, v8, v9
	v_lshlrev_b32_e32 v8, 16, v4
	v_and_b32_e32 v9, 0xffff0000, v4
	v_lshlrev_b32_e32 v4, 16, v5
	v_and_b32_e32 v5, 0xffff0000, v5
	v_lshlrev_b32_e32 v14, 16, v15
	v_and_b32_e32 v15, 0xffff0000, v15
	v_pk_mul_f32 v[4:5], v[4:5], s[48:49] op_sel_hi:[1,0]
	s_mov_b32 s29, 0x2aaaaaab
	v_pk_mul_f32 v[14:15], v[14:15], s[48:49] op_sel_hi:[1,0]
	v_cvt_pk_bf16_f32 v73, v4, v5
	v_mul_hi_i32 v4, v160, s29
	v_cvt_pk_bf16_f32 v67, v14, v15
	v_lshlrev_b32_e32 v14, 16, v10
	v_and_b32_e32 v15, 0xffff0000, v10
	v_lshlrev_b32_e32 v10, 16, v11
	v_and_b32_e32 v11, 0xffff0000, v11
	v_lshrrev_b32_e32 v5, 31, v4
	v_ashrrev_i32_e32 v4, 1, v4
	v_pk_mul_f32 v[10:11], v[10:11], s[48:49] op_sel_hi:[1,0]
	v_add_u32_e32 v45, v4, v5
	v_cvt_pk_bf16_f32 v71, v10, v11
	v_lshlrev_b32_e32 v10, 16, v6
	v_and_b32_e32 v11, 0xffff0000, v6
	v_lshlrev_b32_e32 v6, 16, v7
	v_and_b32_e32 v7, 0xffff0000, v7
	v_mad_u64_u32 v[4:5], s[38:39], v45, -12, v[160:161]
	v_add_u32_e32 v164, 0x200, v160
	v_pk_mul_f32 v[6:7], v[6:7], s[48:49] op_sel_hi:[1,0]
	v_mul_hi_i32 v5, v164, s29
	v_cvt_pk_bf16_f32 v75, v6, v7
	v_lshrrev_b32_e32 v6, 31, v5
	v_ashrrev_i32_e32 v5, 1, v5
	s_mul_i32 s15, s4, 0xcc000
	v_add_u32_e32 v5, v5, v6
	v_pk_mul_f32 v[38:39], v[38:39], s[48:49] op_sel_hi:[1,0]
	v_pk_mul_f32 v[14:15], v[14:15], s[48:49] op_sel_hi:[1,0]
	s_mul_hi_i32 s5, s4, 0xcc000
	s_add_u32 s26, s90, s15
	v_mad_u64_u32 v[6:7], s[38:39], v5, -12, v[164:165]
	v_add_u32_e32 v162, 0x400, v160
	v_cvt_pk_bf16_f32 v66, v38, v39
	v_cvt_pk_bf16_f32 v70, v14, v15
	v_pk_mul_f32 v[8:9], v[8:9], s[48:49] op_sel_hi:[1,0]
	v_pk_mul_f32 v[10:11], v[10:11], s[48:49] op_sel_hi:[1,0]
	s_addc_u32 s27, s91, s5
	v_mul_hi_i32 v7, v162, s29
	v_lshlrev_b32_e32 v14, 3, v4
	v_lshlrev_b32_e32 v38, 3, v6
	v_pk_mul_f32 v[36:37], v[36:37], s[48:49] op_sel_hi:[1,0]
	v_pk_mul_f32 v[12:13], v[12:13], s[48:49] op_sel_hi:[1,0]
	v_cvt_pk_bf16_f32 v72, v8, v9
	v_cvt_pk_bf16_f32 v74, v10, v11
	v_lshrrev_b32_e32 v8, 31, v7
	v_ashrrev_i32_e32 v7, 1, v7
	v_mov_b64_e32 v[10:11], s[26:27]
	v_ashrrev_i32_e32 v15, 31, v14
	v_ashrrev_i32_e32 v39, 31, v38
	v_cvt_pk_bf16_f32 v64, v36, v37
	v_cvt_pk_bf16_f32 v68, v12, v13
	v_add_u32_e32 v7, v7, v8
	v_mad_i64_i32 v[12:13], s[26:27], v45, s17, v[10:11]
	v_lshlrev_b64 v[14:15], 1, v[14:15]
	v_mad_i64_i32 v[36:37], s[26:27], v5, s17, v[10:11]
	v_lshlrev_b64 v[38:39], 1, v[38:39]
	v_mad_u64_u32 v[8:9], s[38:39], v7, -12, v[162:163]
	v_lshl_add_u64 v[12:13], v[12:13], 0, v[14:15]
	v_lshl_add_u64 v[36:37], v[36:37], 0, v[38:39]
	s_barrier
; DI float bflo(unsigned u) { return __uint_as_float(u << 16); }
; DI float bfhi(unsigned u) { return __uint_as_float(u & 0xffff0000u); }
; DI f32x16 zero16() { f32x16 z; for (int i = 0; i < 16; ++i) z[i] = 0.f; return z; }
; DI void phase_attn(const Params& p, int hf, bool skipctx, char* smem, int& rot) {
;     ...
;       const unsigned a1[4] = {qu[4].x, qu[4].y, qu[4].z, qu[4].w}, a2[4] = {qu[5].x, qu[5].y, qu[5].z, qu[5].w};
;       float o1[8], o2[8];
;       const int sq_ = s0 + w * 32 + r;
; #pragma unroll
;       for (int e = 0; e < 8; ++e) {
;         const float x1 = ((e & 1) ? bfhi(a1[e >> 1]) : bflo(a1[e >> 1])) * QSCALE;
;         const float x2 = ((e & 1) ? bfhi(a2[e >> 1]) : bflo(a2[e >> 1])) * QSCALE;
;         float cs = 1.f, sn = 0.f;
;         if (sq_ >= LC) { cs = axc[(sq_ - LC) * 16 + 8 * h + e]; sn = axs[(sq_ - LC) * 16 + 8 * h + e]; }
;         o1[e] = x1 * cs - x2 * sn; o2[e] = x1 * sn + x2 * cs;
;       }
;       qf[4] = pack8(o1[0], o1[1], o1[2], o1[3], o1[4], o1[5], o1[6], o1[7]);
;       qf[5] = pack8(o2[0], o2[1], o2[2], o2[3], o2[4], o2[5], o2[6], o2[7]);
;     }
;     const bf16_t* Kg = Kb + (size_t)(bl * 8 + head) * S * 96;
;     const bf16_t* Vg = VTb + (size_t)(bl * 8 + head) * 64 * S;
;     f32x16 o[2]; o[0] = zero16(); o[1] = zero16();
;     float m_run = -1e30f, l_run = 0.f;
;     uint4 ak0, ak1, ak2, av0, av1, bk0, bk1, bk2, bv0, bv1;
;     const int kr0 = tid / 12, kc0 = tid - kr0 * 12, kr1 = (tid + 512) / 12, kc1 = (tid + 512) - kr1 * 12, kr2 = (tid + 1024) / 12, kc2 = (tid + 1024) - kr2 * 12;
;     const int vr0 = tid >> 4, vr1 = (tid + 512) >> 4, vc = tid & 15;
	global_load_dwordx4 v[76:79], v[12:13], off
	global_load_dwordx4 v[80:83], v[36:37], off
	v_lshlrev_b32_e32 v36, 3, v8
	s_mul_i32 s15, s4, 0x88000
	v_readlane_b32 s36, v252, 5
	v_ashrrev_i32_e32 v37, 31, v36
	s_mul_hi_i32 s5, s4, 0x88000
	v_readlane_b32 s37, v252, 6
	s_add_u32 s36, s36, s15
	v_mad_i64_i32 v[12:13], s[26:27], v7, s17, v[10:11]
	v_lshlrev_b64 v[36:37], 1, v[36:37]
	s_addc_u32 s37, s37, s5
	v_lshl_add_u64 v[12:13], v[12:13], 0, v[36:37]
	v_mov_b32_e32 v40, v42
	v_mov_b32_e32 v41, v16
	v_mov_b32_e32 v16, v43
	v_ashrrev_i32_e32 v9, 4, v160
	v_ashrrev_i32_e32 v50, 4, v164
	global_load_dwordx4 v[84:87], v[12:13], off
	v_mov_b64_e32 v[12:13], s[36:37]
	v_lshlrev_b32_e32 v165, 4, v160
	v_cvt_pk_bf16_f32 v100, v20, v21
	v_add_u32_e32 v20, 0x80, v5
	v_pk_add_f32 v[16:17], v[40:41], v[16:17] neg_lo:[0,1] neg_hi:[0,1]
	v_mad_i64_i32 v[40:41], s[26:27], v9, s16, v[12:13]
	v_and_b32_e32 v42, 0xf0, v165
	v_mov_b32_e32 v43, v221
	v_mad_i64_i32 v[12:13], s[26:27], v50, s16, v[12:13]
	v_cvt_pk_bf16_f32 v98, v18, v19
	v_cvt_pk_bf16_f32 v102, v22, v23
	v_add_u32_e32 v18, 0x80, v45
	v_mad_i64_i32 v[20:21], s[26:27], v20, s17, v[10:11]
	v_add_u32_e32 v22, 0x80, v7
	v_lshl_add_u64 v[40:41], v[40:41], 0, v[42:43]
	v_lshl_add_u64 v[12:13], v[12:13], 0, v[42:43]
	v_mad_i64_i32 v[18:19], s[26:27], v18, s17, v[10:11]
	v_lshl_add_u64 v[20:21], v[20:21], 0, v[38:39]
	v_mad_i64_i32 v[10:11], s[26:27], v22, s17, v[10:11]
	global_load_dwordx4 v[92:95], v[40:41], off
	global_load_dwordx4 v[104:107], v[12:13], off
	v_lshl_add_u64 v[18:19], v[18:19], 0, v[14:15]
	v_lshl_add_u64 v[10:11], v[10:11], 0, v[36:37]
	global_load_dwordx4 v[108:111], v[20:21], off
	global_load_dwordx4 v[116:119], v[10:11], off
	global_load_dwordx4 v[120:123], v[40:41], off offset:256
	global_load_dwordx4 v[112:115], v[18:19], off
	global_load_dwordx4 v[124:127], v[12:13], off offset:256
	v_lshlrev_b32_e32 v46, 16, v0
	v_and_b32_e32 v47, 0xffff0000, v0
	v_lshlrev_b32_e32 v0, 16, v1
	v_and_b32_e32 v1, 0xffff0000, v1
	v_pk_mul_f32 v[30:31], v[30:31], s[48:49] op_sel_hi:[1,0]
	v_pk_add_f32 v[32:33], v[48:49], v[32:33] neg_lo:[0,1] neg_hi:[0,1]
	v_pk_mul_f32 v[0:1], v[0:1], s[48:49] op_sel_hi:[1,0]
	v_lshlrev_b32_e32 v48, 16, v2
	v_and_b32_e32 v49, 0xffff0000, v2
	v_lshlrev_b32_e32 v2, 16, v3
	v_and_b32_e32 v3, 0xffff0000, v3
	v_pk_mul_f32 v[2:3], v[2:3], s[48:49] op_sel_hi:[1,0]
	v_cvt_pk_bf16_f32 v89, v0, v1
	v_pk_mul_f32 v[0:1], v[30:31], v[24:25] op_sel:[0,1] op_sel_hi:[1,0]
	v_cvt_pk_bf16_f32 v91, v2, v3
	v_mov_b32_e32 v2, v28
	v_mov_b32_e32 v3, v0
	v_mov_b32_e32 v0, v29
	v_pk_add_f32 v[0:1], v[2:3], v[0:1] neg_lo:[0,1] neg_hi:[0,1]
	v_pk_mul_f32 v[2:3], v[30:31], v[24:25]
	v_mul_lo_u32 v10, v45, s97
	v_mov_b32_e32 v24, v26
	v_mov_b32_e32 v25, v2
	v_mov_b32_e32 v2, v27
	v_add_u32_e32 v10, 0, v10
	v_lshlrev_b32_e32 v4, 4, v4
	v_pk_add_f32 v[2:3], v[24:25], v[2:3]
	v_add_u32_e32 v176, v10, v4
	v_mul_lo_u32 v4, v5, s97
	v_cvt_pk_bf16_f32 v103, v2, v3
	v_mad_i64_i32 v[2:3], s[26:27], v5, s17, 0
	v_add_u32_e32 v4, 0, v4
	v_lshlrev_b32_e32 v5, 4, v6
	v_cvt_pk_bf16_f32 v96, v16, v17
	v_cvt_pk_bf16_f32 v99, v0, v1
	v_mad_i64_i32 v[0:1], s[26:27], v45, s17, 0
	v_mad_i64_i32 v[16:17], s[26:27], v7, s17, 0
	v_add_u32_e32 v177, v4, v5
	v_mul_lo_u32 v4, v7, s97
	v_add_u32_e32 v4, 0, v4
	v_lshlrev_b32_e32 v5, 4, v8
	s_movk_i32 s26, 0x108
	v_add_u32_e32 v178, v4, v5
	v_mul_lo_u32 v4, v9, s26
	v_add_u32_e32 v5, 0, v4
	s_movk_i32 s27, 0x6800
	v_add3_u32 v179, v5, v42, s27
	v_mul_lo_u32 v5, v50, s26
	v_add_u32_e32 v6, 0, v5
	v_add3_u32 v180, v6, v42, s27
	v_or_b32_e32 v181, 32, v161
	v_or_b32_e32 v182, 64, v161
	v_or_b32_e32 v183, 0x60, v161
	v_readlane_b32 s27, v254, 35
	v_mul_u32_u24_e32 v19, 0x108, v44
	v_mad_u32_u24 v18, v44, s97, 0
	v_add_u32_e32 v21, s27, v4
	v_add_u32_e32 v22, s27, v5
	v_add_u32_e32 v23, s27, v161
	v_add_u32_e32 v24, s27, v181
	v_mov_b32_e32 v4, s27
	v_add_u32_e32 v25, s27, v182
	v_add_u32_e32 v26, s27, v183
	v_readlane_b32 s27, v254, 36
	v_mad_u32_u24 v184, v44, s26, v4
	v_add_u32_e32 v20, 0, v161
	v_mov_b32_e32 v4, s27
	v_mad_u32_u24 v185, v44, s26, v4
	s_add_u32 s26, s15, 0x1a49c300
	v_add_u32_e32 v27, s27, v161
	v_add_u32_e32 v28, s27, v181
	v_add_u32_e32 v29, s27, v182
	v_add_u32_e32 v30, s27, v183
	s_addc_u32 s27, s5, 0
	v_mov_b64_e32 v[4:5], s[26:27]
	v_mad_i64_i32 v[166:167], s[26:27], v9, s16, v[4:5]
	v_mad_i64_i32 v[168:169], s[26:27], v50, s16, v[4:5]
	v_mad_i64_i32 v[4:5], s[26:27], s4, v231, v[16:17]
	v_mad_i64_i32 v[2:3], s[26:27], s4, v231, v[2:3]
	v_mad_i64_i32 v[0:1], s[4:5], s4, v231, v[0:1]
	v_lshl_add_u64 v[174:175], v[0:1], 0, v[14:15]
	v_mov_b32_e32 v14, v221
	v_mov_b32_e32 v15, v221
	v_add_u32_e32 v186, v21, v42
	v_add_u32_e32 v187, v22, v42
	v_add_u32_e32 v188, v23, v19
	v_add_u32_e32 v16, v24, v19
	v_add_u32_e32 v17, v25, v19
	v_add_u32_e32 v21, v26, v19
	v_add_u32_e32 v22, v28, v19
	v_add_u32_e32 v23, v29, v19
	v_add_u32_e32 v24, v30, v19
	v_pk_mul_f32 v[46:47], v[46:47], s[48:49] op_sel_hi:[1,0]
	v_pk_mul_f32 v[48:49], v[48:49], s[48:49] op_sel_hi:[1,0]
	v_lshl_add_u64 v[170:171], v[4:5], 0, v[36:37]
	v_lshl_add_u64 v[172:173], v[2:3], 0, v[38:39]
	v_mov_b32_e32 v0, v221
	v_mov_b32_e32 v1, v221
	v_mov_b32_e32 v2, v221
	v_mov_b32_e32 v3, v221
	v_mov_b32_e32 v4, v221
	v_mov_b32_e32 v5, v221
	v_mov_b32_e32 v6, v221
	v_mov_b32_e32 v7, v221
	v_mov_b32_e32 v8, v221
	v_mov_b32_e32 v9, v221
	v_mov_b32_e32 v10, v221
	v_mov_b32_e32 v11, v221
	v_mov_b32_e32 v12, v221
	v_mov_b32_e32 v13, v221
	v_add_u32_e32 v189, v27, v19
	v_add_u32_e32 v190, v18, v220
	v_add_u32_e32 v191, v20, v19
	v_add_u32_e32 v194, 0x2000, v16
	v_add_u32_e32 v204, 0x2000, v17
	v_add_u32_e32 v206, 0x2000, v21
	v_add_u32_e32 v208, 0x2000, v22
	v_add_u32_e32 v210, 0x2000, v23
	v_add_u32_e32 v211, 0x2000, v24
	v_mov_b64_e32 v[30:31], v[14:15]
	v_cvt_pk_bf16_f32 v88, v46, v47
	v_cvt_pk_bf16_f32 v90, v48, v49
	v_cvt_pk_bf16_f32 v97, v32, v33
	v_cvt_pk_bf16_f32 v101, v34, v35
	v_or_b32_e32 v166, v166, v42
	v_or_b32_e32 v168, v168, v42
	s_mov_b32 s4, 0
	v_mov_b32_e32 v212, 0xf149f2ca
	v_mov_b32_e32 v213, 0
	v_mov_b64_e32 v[28:29], v[12:13]
	v_mov_b64_e32 v[26:27], v[10:11]
	v_mov_b64_e32 v[24:25], v[8:9]
	v_mov_b64_e32 v[22:23], v[6:7]
	v_mov_b64_e32 v[20:21], v[4:5]
	v_mov_b64_e32 v[18:19], v[2:3]
	v_mov_b64_e32 v[16:17], v[0:1]
	v_and_b32_e32 v200, 15, v192
	v_lshrrev_b32_e32 v201, 4, v192
	v_mul_u32_u24_e32 v179, 0x110, v201
	v_lshrrev_b32_e32 v202, 1, v200
	v_lshl_add_u32 v179, v202, 5, v179
	v_and_b32_e32 v202, 1, v200
	v_lshl_add_u32 v179, v202, 3, v179
	v_add_u32_e32 v179, 0x6800, v179
	v_add_u32_e32 v180, 0x2200, v179
	v_add_u32_e32 v186, 0xac00, v179
	v_add_u32_e32 v187, 0xac00, v180
	v_and_b32_e32 v200, 31, v192
	v_bfe_u32 v201, v192, 5, 1
	v_mul_u32_u24_e32 v191, 0x110, v200
	v_lshl_add_u32 v191, v201, 4, v191
	v_add_u32_e32 v191, 0x6800, v191
	s_waitcnt vmcnt(9)
; DI f32x16 zero16() { f32x16 z; for (int i = 0; i < 16; ++i) z[i] = 0.f; return z; }
; DI void phase_attn(const Params& p, int hf, bool skipctx, char* smem, int& rot) {
;     ...
;     f32x16 o[2]; o[0] = zero16(); o[1] = zero16();
;     float m_run = -1e30f, l_run = 0.f;
;     uint4 ak0, ak1, ak2, av0, av1, bk0, bk1, bk2, bv0, bv1;
;     const int kr0 = tid / 12, kc0 = tid - kr0 * 12, kr1 = (tid + 512) / 12, kc1 = (tid + 512) - kr1 * 12, kr2 = (tid + 1024) / 12, kc2 = (tid + 1024) - kr2 * 12;
;     const int vr0 = tid >> 4, vr1 = (tid + 512) >> 4, vc = tid & 15;
;     ...
;     ATT_WRITE(ak0, ak1, ak2, av0, av1, 0);
;     __syncthreads();
	ds_write_b128 v176, v[76:79]
	s_waitcnt vmcnt(8)
	ds_write_b128 v177, v[80:83]
	s_waitcnt vmcnt(7)
	ds_write_b128 v178, v[84:87]
	s_waitcnt vmcnt(6)
	ds_write_b64 v179, v[92:93] offset:0
	ds_write_b64 v179, v[94:95] offset:16
	s_waitcnt vmcnt(5)
	ds_write_b64 v179, v[104:105] offset:8704
	ds_write_b64 v179, v[106:107] offset:8720
	s_waitcnt lgkmcnt(0)
	s_barrier
	v_mov_b32_e32 v194, v176
	v_mov_b32_e32 v204, v177
	v_mov_b32_e32 v206, v178
	v_mov_b32_e32 v208, v179
	v_mov_b32_e32 v210, v190
	v_mov_b32_e32 v211, v191
	v_mov_b32_e32 v220, 0xf149f2ca
	v_mov_b32_e32 v176, 0
	v_mov_b32_e32 v177, 0
	v_mov_b32_e32 v178, 0
	v_mov_b32_e32 v179, 0
	v_mov_b32_e32 v180, 0
	v_mov_b32_e32 v181, 0
	v_mov_b32_e32 v182, 0
	v_mov_b32_e32 v183, 0
	v_mov_b32_e32 v184, 0
	v_mov_b32_e32 v185, 0
	v_mov_b32_e32 v186, 0
	v_mov_b32_e32 v187, 0
	v_mov_b32_e32 v188, 0
	v_mov_b32_e32 v189, 0
	v_mov_b32_e32 v190, 0
	v_mov_b32_e32 v191, 0
	v_add_u32_e32 v170, 0x18b28000, v170
	v_add_u32_e32 v172, 0x18b28000, v172
	v_add_u32_e32 v174, 0x18b28000, v174
	v_mov_b32_e32 v167, 0xbf800000
